# K-loop segment-edge trimming + GLA prologue load hoisting + logdecay LDS reads software-pipelined (8 in flight)
# speedup vs baseline: 1.0116x; 1.0057x over previous
; __device__ __forceinline__ int tid_now() { int t = threadIdx.x; asm volatile("" : "+v"(t)); return t; }
; #define LAS __attribute__((address_space(3)))
; __device__ __forceinline__ void gla_stage_glr(LAS float* glrs, const float* glr, int R0, int tid) { if (tid < 256) *(LAS f32x4*)(glrs + tid * 4) = *(const f32x4*)(glr + (size_t)R0 * 16 + tid * 4); }
; __device__ __forceinline__ void gla_stepC(LAS unsigned char* lds, int item, const bf16* proj, const bf16* vtg, const float* glr, const float* W2, const float* b2, const bf16* sT, const float* gout, bf16* mix) {
;     const int tid = tid_now(), lane = tid & 63, w = tid >> 6, fr = lane & 15, fq = lane >> 4;
;     const int bb = item >> 7, hg = (item >> 5) & 3, n = item & 31, R0 = bb * SEQ + n * 64;
;     LAS bf16* QE = (LAS bf16*)(lds + GL_QE); LAS bf16* KE = (LAS bf16*)(lds + GL_KE); LAS bf16* VT = (LAS bf16*)(lds + GL_VT); LAS bf16* AS = (LAS bf16*)(lds + GL_AS);
;     LAS float* tot = (LAS float*)(lds + GL_TOT); LAS float* red = (LAS float*)(lds + GL_RED); LAS float* glrs = (LAS float*)(lds + GL_GLR);
;     const int d = tid & 127, g = tid >> 7;
;     float wcol[16];
; #pragma unroll
;     for (int r = 0; r < 16; ++r) wcol[r] = W2[r * 512 + hg * 128 + d];
;     const float wbias = b2[hg * 128 + d];
;     const bf16* sp = sT + (size_t)item * 32768;
;     bf16x8 sfr[4][2];
; #pragma unroll
;     for (int ks = 0; ks < 4; ++ks)
; #pragma unroll
;         for (int eb = 0; eb < 2; ++eb) sfr[ks][eb] = *(const bf16x8*)(sp + (size_t)(32 * w + 16 * eb + fr) * 128 + 32 * ks + 8 * fq);
;     u32x2 rgv[4][2]; f32x4 gnv[2];
; #pragma unroll
;     for (int eb = 0; eb < 2; ++eb) { gnv[eb] = *(const f32x4*)(gout + 32 * w + 16 * eb + 4 * fq);
; #pragma unroll
;         for (int ib = 0; ib < 4; ++ib) rgv[ib][eb] = *(const u32x2*)(proj + (size_t)(R0 + 16 * ib + fr) * PROJW + 5120 + hg * 256 + 32 * w + 16 * eb + 4 * fq); }
;     gla_stage_glr(glrs, glr, R0, tid);
.LBB0_78:
	v_readlane_b32 s0, v255, 16
	v_mov_b32_e32 v55, v176
	s_bfe_u32 s46, s45, 0x20005
	v_mov_b32_e32 v0, s0
	s_waitcnt lgkmcnt(0)
	ds_read_b128 v[0:3], v0
	v_readlane_b32 s0, v255, 17
	s_movk_i32 s22, 0x2000
	s_movk_i32 s15, 0x4000
	s_lshl_b32 s26, s46, 9
	s_waitcnt lgkmcnt(0)
	v_readfirstlane_b32 s16, v0
	v_mov_b32_e32 v0, s0
	v_readfirstlane_b32 s17, v1
	ds_read_b64 v[0:1], v0
	v_readfirstlane_b32 s40, v2
	v_and_b32_e32 v43, 0x7f, v55
	v_readfirstlane_b32 s41, v3
	s_waitcnt lgkmcnt(0)
	v_readfirstlane_b32 s14, v0
	v_ashrrev_i32_e32 v42, 1, v55
	v_and_b32_e32 v47, 15, v55
	v_mov_b32_e32 v0, s14
	s_lshl_b32 s14, s46, 7
	v_or_b32_e32 v2, s14, v43
	v_lshlrev_b32_e32 v152, 2, v2
	v_lshl_add_u64 v[2:3], s[16:17], 0, v[152:153]
	v_add_co_u32_e32 v4, vcc, s95, v2
	global_load_dword v79, v152, s[16:17]
	global_load_dword v80, v152, s[16:17] offset:2048
	v_addc_co_u32_e32 v5, vcc, 0, v3, vcc
	v_add_co_u32_e32 v6, vcc, s22, v2
	v_and_b32_e32 v62, 0xffffffe0, v42
	s_nop 0
	v_addc_co_u32_e32 v7, vcc, 0, v3, vcc
	global_load_dword v83, v[6:7], off offset:-4096
	global_load_dword v84, v[4:5], off offset:2048
	global_load_dword v71, v[6:7], off
	global_load_dword v72, v[6:7], off offset:2048
	v_add_co_u32_e32 v4, vcc, s97, v2
	v_or_b32_e32 v40, v62, v47
	s_nop 0
	v_addc_co_u32_e32 v5, vcc, 0, v3, vcc
	v_add_co_u32_e32 v6, vcc, s15, v2
	s_movk_i32 s15, 0x5000
	s_nop 0
	v_addc_co_u32_e32 v7, vcc, 0, v3, vcc
	global_load_dword v77, v[6:7], off offset:-4096
	global_load_dword v78, v[4:5], off offset:2048
	global_load_dword v73, v[6:7], off
	global_load_dword v75, v[6:7], off offset:2048
	v_add_co_u32_e32 v4, vcc, s15, v2
	s_movk_i32 s15, 0x6000
	s_nop 0
	v_addc_co_u32_e32 v5, vcc, 0, v3, vcc
	v_add_co_u32_e32 v6, vcc, s15, v2
	s_movk_i32 s15, 0x7000
	s_nop 0
	v_addc_co_u32_e32 v7, vcc, 0, v3, vcc
	global_load_dword v81, v[6:7], off offset:-4096
	global_load_dword v82, v[4:5], off offset:2048
	global_load_dword v67, v[6:7], off
	global_load_dword v70, v[6:7], off offset:2048
	v_add_co_u32_e32 v2, vcc, s15, v2
	v_or_b32_e32 v4, 16, v40
	v_readfirstlane_b32 s0, v1
	v_bfe_u32 v61, v55, 4, 2
	v_addc_co_u32_e32 v3, vcc, 0, v3, vcc
	s_ashr_i32 s15, s45, 7
	v_ashrrev_i32_e32 v41, 31, v40
	v_ashrrev_i32_e32 v5, 31, v4
	v_mov_b32_e32 v1, s0
	s_and_b32 s0, s44, 0x7c0
	global_load_dword v76, v[2:3], off
	global_load_dword v74, v[2:3], off offset:2048
	s_lshl_b32 s16, s15, 11
	global_load_dword v85, v152, s[40:41]
	v_lshlrev_b64 v[2:3], 8, v[40:41]
	v_lshlrev_b32_e32 v152, 4, v61
	v_lshlrev_b64 v[4:5], 8, v[4:5]
	s_or_b32 s36, s16, s0
	v_or_b32_e32 v2, v2, v152
	v_or_b32_e32 v4, v4, v152
	v_ashrrev_i32_e32 v63, 31, v62
	v_lshl_add_u64 v[2:3], s[42:43], 0, v[2:3]
	v_lshl_add_u64 v[4:5], s[42:43], 0, v[4:5]
	v_lshl_add_u64 v[0:1], v[62:63], 2, v[0:1]
	v_or_b32_e32 v66, s36, v47
	v_mov_b64_e32 v[6:7], s[38:39]
	global_load_dwordx4 v[32:35], v[2:3], off offset:-192
	global_load_dwordx4 v[36:39], v[4:5], off offset:-192
	global_load_dwordx4 v[24:27], v[2:3], off offset:-128
	global_load_dwordx4 v[28:31], v[4:5], off offset:-128
	global_load_dwordx4 v[16:19], v[2:3], off offset:-64
	global_load_dwordx4 v[20:23], v[4:5], off offset:-64
	global_load_dwordx4 v[8:11], v[2:3], off
	global_load_dwordx4 v[12:15], v[4:5], off
	v_lshl_add_u64 v[4:5], v[0:1], 0, v[152:153]
	v_mad_i64_i32 v[0:1], s[16:17], v66, s97, v[6:7]
	v_lshl_add_u64 v[0:1], v[0:1], 0, s[26:27]
	v_lshlrev_b64 v[44:45], 1, v[62:63]
	v_lshl_add_u64 v[48:49], v[0:1], 0, v[44:45]
	v_lshlrev_b32_e32 v50, 3, v61
	v_mov_b32_e32 v51, v153
	v_lshl_add_u64 v[48:49], v[48:49], 0, v[50:51]
	s_mov_b64 s[40:41], 0x2800
	v_lshl_add_u64 v[56:57], v[48:49], 0, s[40:41]
	v_add_co_u32_e32 v48, vcc, s22, v48
	v_or_b32_e32 v60, 16, v66
	s_nop 0
	v_addc_co_u32_e32 v49, vcc, 0, v49, vcc
	global_load_dwordx2 v[68:69], v[48:49], off offset:2048
	v_mad_i64_i32 v[48:49], s[16:17], v60, s97, v[6:7]
	v_lshl_add_u64 v[48:49], v[48:49], 0, s[26:27]
	v_lshl_add_u64 v[48:49], v[48:49], 0, v[44:45]
	v_lshl_add_u64 v[48:49], v[48:49], 0, v[50:51]
	v_lshl_add_u64 v[86:87], v[48:49], 0, s[40:41]
	v_add_co_u32_e32 v48, vcc, s22, v48
	v_or_b32_e32 v54, 32, v66
	s_nop 0
	v_addc_co_u32_e32 v49, vcc, 0, v49, vcc
	global_load_dwordx2 v[58:59], v[48:49], off offset:2048
	v_mad_i64_i32 v[48:49], s[16:17], v54, s97, v[6:7]
	v_lshl_add_u64 v[48:49], v[48:49], 0, s[26:27]
	v_or_b32_e32 v46, 48, v66
	v_lshl_add_u64 v[48:49], v[48:49], 0, v[44:45]
	v_mad_i64_i32 v[6:7], s[16:17], v46, s97, v[6:7]
	v_lshl_add_u64 v[48:49], v[48:49], 0, v[50:51]
	v_lshl_add_u64 v[6:7], v[6:7], 0, s[26:27]
	v_lshl_add_u64 v[88:89], v[48:49], 0, s[40:41]
	v_add_co_u32_e32 v48, vcc, s22, v48
	v_lshl_add_u64 v[6:7], v[6:7], 0, v[44:45]
	s_nop 0
	v_addc_co_u32_e32 v49, vcc, 0, v49, vcc
	v_lshl_add_u64 v[6:7], v[6:7], 0, v[50:51]
	v_lshl_add_u64 v[44:45], v[6:7], 0, s[40:41]
	v_add_co_u32_e32 v6, vcc, 0x2000, v6
	global_load_dwordx4 v[0:3], v[4:5], off
	s_nop 0
	v_addc_co_u32_e32 v7, vcc, 0, v7, vcc
	global_load_dwordx2 v[52:53], v[48:49], off offset:2048
	s_nop 0
	global_load_dwordx2 v[48:49], v[6:7], off offset:2048
	s_nop 0
	global_load_dwordx4 v[4:7], v[4:5], off offset:64
	s_nop 0
	global_load_dwordx2 v[64:65], v[56:57], off offset:32
	s_nop 0
	global_load_dwordx2 v[56:57], v[86:87], off offset:32
	global_load_dwordx2 v[50:51], v[88:89], off offset:32
	s_nop 0
	global_load_dwordx2 v[44:45], v[44:45], off offset:32
	s_movk_i32 s16, 0x100
	v_cmp_gt_i32_e32 vcc, s16, v55
	s_ashr_i32 s37, s36, 31
	s_and_saveexec_b64 s[40:41], vcc
	s_cbranch_execz .LBB0_80
	s_lshl_b64 s[16:17], s[36:37], 6
	v_lshlrev_b32_e32 v86, 2, v55
	s_add_u32 s16, s48, s16
	s_addc_u32 s17, s49, s17
	v_ashrrev_i32_e32 v87, 31, v86
	v_lshl_add_u64 v[86:87], v[86:87], 2, s[16:17]
	global_load_dwordx4 v[104:107], v[86:87], off
	v_lshl_add_u32 v124, v55, 4, 0
	v_add_u32_e32 v124, 0x15400, v124
; __device__ __forceinline__ int tid_now() { int t = threadIdx.x; asm volatile("" : "+v"(t)); return t; }
; #define LAS __attribute__((address_space(3)))
; __device__ __forceinline__ void gla_logdecay(float (&b)[16], float& blast, const LAS float* glrs, const float (&wcol)[16], const float bias, int d, int g, LAS float* tot) {
;     float run = 0.f;
; #pragma unroll
;     for (int ii = 0; ii < 16; ++ii) { const LAS f32x4* gr = (const LAS f32x4*)(glrs + (16 * g + ii) * 16); float z = bias;
; #pragma unroll
;         for (int r4 = 0; r4 < 4; ++r4) { const f32x4 gv = gr[r4]; z += gv[0] * wcol[4 * r4] + gv[1] * wcol[4 * r4 + 1] + gv[2] * wcol[4 * r4 + 2] + gv[3] * wcol[4 * r4 + 3]; }
;         const float la = -(fmaxf(-z, 0.f) + __logf(1.0f + __expf(-fabsf(z)))) * (1.0f / 16.0f);
;         run += la; b[ii] = run; }
; __device__ __forceinline__ void gla_load_vt(LAS bf16* VT, const bf16* vsrc  ) {
;     const int tid = tid_now(), e = tid >> 1, hf = tid & 1;
;     const bf16* p = vsrc + (size_t)e * SEQ + 32 * hf;
; #pragma unroll
;     for (int q = 0; q < 4; ++q) *(LAS u32x4*)(VT + e * VP + 32 * hf + 8 * q) = *(const u32x4*)(p + 8 * q);
; }
.LBB0_80:
	s_or_b64 exec, exec, s[40:41]
	s_mul_i32 s17, s36, 0x3000
	s_mul_hi_i32 s16, s36, 0x3000
	s_add_u32 s17, s38, s17
	s_addc_u32 s16, s39, s16
	s_lshl_b32 s14, s14, 1
	s_add_u32 s14, s17, s14
	s_addc_u32 s22, s16, 0
	s_add_u32 s16, s14, 0x1800
	s_addc_u32 s17, s22, 0
	v_ashrrev_i32_e32 v94, 3, v55
	v_mov_b64_e32 v[86:87], s[16:17]
	v_lshlrev_b32_e32 v88, 4, v55
	v_mad_i64_i32 v[86:87], s[16:17], v94, s97, v[86:87]
	v_and_b32_e32 v90, 0x70, v88
	v_mov_b32_e32 v91, v153
	v_lshl_add_u64 v[92:93], v[86:87], 0, v[90:91]
	global_load_dwordx4 v[108:111], v[92:93], off
	v_mul_lo_u32 v95, v94, s94
	v_add3_u32 v95, 0, v95, v90
	s_add_u32 s16, s14, 0x1c00
	s_addc_u32 s17, s22, 0
	s_lshl_b32 s14, s15, 2
	s_or_b32 s14, s14, s46
	s_ashr_i32 s15, s14, 31
	s_lshl_b64 s[14:15], s[14:15], 20
	s_add_u32 s14, s71, s14
	s_addc_u32 s15, s80, s15
	s_lshl_b32 s0, s0, 1
	s_add_u32 s14, s14, s0
	s_addc_u32 s15, s15, 0
	v_ashrrev_i32_e32 v41, 7, v55
	s_mov_b32 s0, 0xbd800000
	v_lshlrev_b32_e32 v63, 2, v61
	global_load_dwordx4 v[112:115], v[92:93], off offset:128
	v_mov_b64_e32 v[86:87], s[16:17]
	v_mad_i64_i32 v[86:87], s[16:17], v94, s97, v[86:87]
	v_lshl_add_u64 v[90:91], v[86:87], 0, v[90:91]
	global_load_dwordx4 v[116:119], v[90:91], off
	s_movk_i32 s16, 0x90
	global_load_dwordx4 v[120:123], v[90:91], off offset:128
	v_mov_b32_e32 v90, v176
	v_mov_b32_e32 v91, v153
	s_nop 0
	v_ashrrev_i32_e32 v86, 1, v90
	v_ashrrev_i32_e32 v87, 31, v86
	v_lshlrev_b64 v[88:89], 12, v[86:87]
	v_lshlrev_b32_e32 v87, 6, v90
	v_lshl_add_u64 v[88:89], s[14:15], 0, v[88:89]
	v_and_b32_e32 v90, 64, v87
	v_lshl_add_u64 v[98:99], v[88:89], 0, v[90:91]
	v_mul_lo_u32 v86, v86, s16
	v_add3_u32 v102, 0, v86, v90
	global_load_dwordx4 v[128:131], v[98:99], off offset:48
	global_load_dwordx4 v[132:135], v[98:99], off offset:32
	global_load_dwordx4 v[136:139], v[98:99], off offset:16
	global_load_dwordx4 v[140:143], v[98:99], off
	v_cmp_gt_i32_e32 vcc, 0x100, v55
	s_waitcnt vmcnt(0)
	s_nop 0
	s_and_saveexec_b64 s[40:41], vcc
	ds_write_b128 v124, v[104:107]
	s_or_b64 exec, exec, s[40:41]
	ds_write_b128 v95, v[108:111]
	ds_write_b128 v95, v[112:115] offset:128
	ds_write_b128 v95, v[116:119] offset:18432
	ds_write_b128 v95, v[120:123] offset:18560
	ds_write_b128 v102, v[140:143] offset:36864
	ds_write_b128 v102, v[136:139] offset:36880
	ds_write_b128 v102, v[132:135] offset:36896
	ds_write_b128 v102, v[128:131] offset:36912
	v_lshl_add_u32 v86, v41, 10, 0
	v_add_u32_e32 v87, 0x15400, v86
	s_waitcnt lgkmcnt(0)
	s_barrier
	ds_read_b128 v[114:117], v87
	ds_read_b128 v[118:121], v87 offset:16
	ds_read_b128 v[122:125], v87 offset:32
	ds_read_b128 v[126:129], v87 offset:48
	ds_read_b128 v[130:133], v87 offset:64
	ds_read_b128 v[134:137], v87 offset:80
	ds_read_b128 v[138:141], v87 offset:96
	ds_read_b128 v[142:145], v87 offset:112
	s_waitcnt lgkmcnt(7)
	v_mul_f32_e32 v86, v80, v115
	v_fmac_f32_e32 v86, v79, v114
	s_waitcnt lgkmcnt(6)
	v_mul_f32_e32 v88, v72, v119
	v_fmac_f32_e32 v86, v83, v116
	v_fmac_f32_e32 v88, v71, v118
	v_fmac_f32_e32 v86, v84, v117
	ds_read_b128 v[114:117], v87 offset:128
	v_fmac_f32_e32 v88, v77, v120
	v_add_f32_e32 v86, v85, v86
	v_fmac_f32_e32 v88, v78, v121
	ds_read_b128 v[118:121], v87 offset:144
	v_add_f32_e32 v86, v86, v88
	s_waitcnt lgkmcnt(7)
	v_mul_f32_e32 v88, v75, v123
	v_fmac_f32_e32 v88, v73, v122
	v_fmac_f32_e32 v88, v81, v124
	v_fmac_f32_e32 v88, v82, v125
	ds_read_b128 v[122:125], v87 offset:160
	v_add_f32_e32 v86, v86, v88
	s_waitcnt lgkmcnt(7)
	v_mul_f32_e32 v88, v70, v127
	v_fmac_f32_e32 v88, v67, v126
	v_fmac_f32_e32 v88, v76, v128
	v_fmac_f32_e32 v88, v74, v129
	ds_read_b128 v[126:129], v87 offset:176
	v_add_f32_e32 v86, v86, v88
	v_max_f32_e64 v88, -v86, 0
	v_mul_f32_e64 v86, |v86|, s64
	v_exp_f32_e32 v86, v86
	s_nop 0
	v_add_f32_e32 v86, 1.0, v86
	v_cmp_gt_f32_e32 vcc, s65, v86
	s_nop 1
	v_cndmask_b32_e64 v89, 0, 32, vcc
	v_ldexp_f32 v86, v86, v89
	v_log_f32_e32 v86, v86
	s_nop 0
	v_mul_f32_e32 v89, 0x3f317217, v86
	v_fma_f32 v89, v86, s66, -v89
	v_fmac_f32_e32 v89, 0x3377d1cf, v86
	v_fmac_f32_e32 v89, 0x3f317217, v86
	v_cmp_lt_f32_e64 s[40:41], |v86|, s67
	s_nop 1
	v_cndmask_b32_e64 v86, v86, v89, s[40:41]
	v_cndmask_b32_e32 v89, 0, v252, vcc
	v_sub_f32_e32 v86, v86, v89
	v_add_f32_e32 v86, v88, v86
	v_fma_f32 v86, v86, s0, 0
	s_movk_i32 s0, 0x900
	s_waitcnt lgkmcnt(7)
	v_mul_f32_e32 v89, v80, v131
	v_fmac_f32_e32 v89, v79, v130
	v_fmac_f32_e32 v89, v83, v132
	v_fmac_f32_e32 v89, v84, v133
	ds_read_b128 v[130:133], v87 offset:192
	v_add_f32_e32 v92, v85, v89
	s_waitcnt lgkmcnt(7)
	v_mul_f32_e32 v89, v72, v135
	v_fmac_f32_e32 v89, v71, v134
	v_fmac_f32_e32 v89, v77, v136
	v_fmac_f32_e32 v89, v78, v137
	ds_read_b128 v[134:137], v87 offset:208
	v_add_f32_e32 v92, v92, v89
	s_waitcnt lgkmcnt(7)
	v_mul_f32_e32 v89, v75, v139
	v_fmac_f32_e32 v89, v73, v138
	v_fmac_f32_e32 v89, v81, v140
	v_fmac_f32_e32 v89, v82, v141
	ds_read_b128 v[138:141], v87 offset:224
	v_add_f32_e32 v92, v92, v89
	s_waitcnt lgkmcnt(7)
	v_mul_f32_e32 v89, v70, v143
	v_fmac_f32_e32 v89, v67, v142
	v_fmac_f32_e32 v89, v76, v144
	v_fmac_f32_e32 v89, v74, v145
	ds_read_b128 v[142:145], v87 offset:240
	v_add_f32_e32 v88, v92, v89
	v_max_f32_e64 v89, -v88, 0
	v_mul_f32_e64 v88, |v88|, s64
	v_exp_f32_e32 v88, v88
	s_nop 0
	v_add_f32_e32 v88, 1.0, v88
	v_cmp_gt_f32_e32 vcc, s65, v88
	s_nop 1
	v_cndmask_b32_e64 v90, 0, 32, vcc
	v_ldexp_f32 v88, v88, v90
	v_log_f32_e32 v88, v88
	s_nop 0
	v_mul_f32_e32 v90, 0x3f317217, v88
	v_fma_f32 v90, v88, s66, -v90
	v_fmac_f32_e32 v90, 0x3377d1cf, v88
	v_fmac_f32_e32 v90, 0x3f317217, v88
	v_cmp_lt_f32_e64 s[40:41], |v88|, s67
	s_nop 1
	v_cndmask_b32_e64 v88, v88, v90, s[40:41]
	v_cndmask_b32_e32 v90, 0, v252, vcc
	v_sub_f32_e32 v88, v88, v90
	v_add_f32_e32 v88, v89, v88
	v_fmamk_f32 v88, v88, 0xbd800000, v86
	s_waitcnt lgkmcnt(7)
; #define LAS __attribute__((address_space(3)))
; __device__ __forceinline__ void gla_logdecay(float (&b)[16], float& blast, const LAS float* glrs, const float (&wcol)[16], const float bias, int d, int g, LAS float* tot) {
;     float run = 0.f;
; #pragma unroll
;     for (int ii = 0; ii < 16; ++ii) { const LAS f32x4* gr = (const LAS f32x4*)(glrs + (16 * g + ii) * 16); float z = bias;
; #pragma unroll
;         for (int r4 = 0; r4 < 4; ++r4) { const f32x4 gv = gr[r4]; z += gv[0] * wcol[4 * r4] + gv[1] * wcol[4 * r4 + 1] + gv[2] * wcol[4 * r4 + 2] + gv[3] * wcol[4 * r4 + 3]; }
;         const float la = -(fmaxf(-z, 0.f) + __logf(1.0f + __expf(-fabsf(z)))) * (1.0f / 16.0f);
;         run += la; b[ii] = run; }
	v_mul_f32_e32 v89, v80, v115
	v_fmac_f32_e32 v89, v79, v114
	v_fmac_f32_e32 v89, v83, v116
	v_fmac_f32_e32 v89, v84, v117
	ds_read_b128 v[114:117], v87 offset:256
	v_add_f32_e32 v89, v85, v89
	s_waitcnt lgkmcnt(7)
	v_mul_f32_e32 v91, v72, v119
	v_fmac_f32_e32 v91, v71, v118
	v_fmac_f32_e32 v91, v77, v120
	v_fmac_f32_e32 v91, v78, v121
	ds_read_b128 v[118:121], v87 offset:272
	v_add_f32_e32 v89, v89, v91
	s_waitcnt lgkmcnt(7)
	v_mul_f32_e32 v91, v75, v123
	v_fmac_f32_e32 v91, v73, v122
	v_fmac_f32_e32 v91, v81, v124
	v_fmac_f32_e32 v91, v82, v125
	ds_read_b128 v[122:125], v87 offset:288
	v_add_f32_e32 v89, v89, v91
	s_waitcnt lgkmcnt(7)
	v_mul_f32_e32 v91, v70, v127
	v_fmac_f32_e32 v91, v67, v126
	v_fmac_f32_e32 v91, v76, v128
	v_fmac_f32_e32 v91, v74, v129
	ds_read_b128 v[126:129], v87 offset:304
	v_add_f32_e32 v89, v89, v91
	v_max_f32_e64 v90, -v89, 0
	v_mul_f32_e64 v89, |v89|, s64
	v_exp_f32_e32 v89, v89
	s_nop 0
	v_add_f32_e32 v89, 1.0, v89
	v_cmp_gt_f32_e32 vcc, s65, v89
	s_nop 1
	v_cndmask_b32_e64 v91, 0, 32, vcc
	v_ldexp_f32 v89, v89, v91
	v_log_f32_e32 v89, v89
	s_nop 0
	v_mul_f32_e32 v91, 0x3f317217, v89
	v_fma_f32 v91, v89, s66, -v91
	v_fmac_f32_e32 v91, 0x3377d1cf, v89
	v_fmac_f32_e32 v91, 0x3f317217, v89
	v_cmp_lt_f32_e64 s[40:41], |v89|, s67
	s_nop 1
	v_cndmask_b32_e64 v89, v89, v91, s[40:41]
	v_cndmask_b32_e32 v91, 0, v252, vcc
	v_sub_f32_e32 v89, v89, v91
	v_add_f32_e32 v89, v90, v89
	v_fmamk_f32 v89, v89, 0xbd800000, v88
	s_waitcnt lgkmcnt(7)
	v_mul_f32_e32 v91, v80, v131
	v_fmac_f32_e32 v91, v79, v130
	v_fmac_f32_e32 v91, v83, v132
	v_fmac_f32_e32 v91, v84, v133
	ds_read_b128 v[130:133], v87 offset:320
	v_add_f32_e32 v94, v85, v91
	s_waitcnt lgkmcnt(7)
	v_mul_f32_e32 v91, v72, v135
	v_fmac_f32_e32 v91, v71, v134
	v_fmac_f32_e32 v91, v77, v136
	v_fmac_f32_e32 v91, v78, v137
	ds_read_b128 v[134:137], v87 offset:336
	v_add_f32_e32 v94, v94, v91
	s_waitcnt lgkmcnt(7)
	v_mul_f32_e32 v91, v75, v139
	v_fmac_f32_e32 v91, v73, v138
	v_fmac_f32_e32 v91, v81, v140
	v_fmac_f32_e32 v91, v82, v141
	ds_read_b128 v[138:141], v87 offset:352
	v_add_f32_e32 v94, v94, v91
	s_waitcnt lgkmcnt(7)
	v_mul_f32_e32 v91, v70, v143
	v_fmac_f32_e32 v91, v67, v142
	v_fmac_f32_e32 v91, v76, v144
	v_fmac_f32_e32 v91, v74, v145
	ds_read_b128 v[142:145], v87 offset:368
	v_add_f32_e32 v90, v94, v91
	v_max_f32_e64 v91, -v90, 0
	v_mul_f32_e64 v90, |v90|, s64
	v_exp_f32_e32 v90, v90
	s_nop 0
	v_add_f32_e32 v90, 1.0, v90
	v_cmp_gt_f32_e32 vcc, s65, v90
	s_nop 1
	v_cndmask_b32_e64 v92, 0, 32, vcc
	v_ldexp_f32 v90, v90, v92
	v_log_f32_e32 v90, v90
	s_nop 0
	v_mul_f32_e32 v92, 0x3f317217, v90
	v_fma_f32 v92, v90, s66, -v92
	v_fmac_f32_e32 v92, 0x3377d1cf, v90
	v_fmac_f32_e32 v92, 0x3f317217, v90
	v_cmp_lt_f32_e64 s[40:41], |v90|, s67
	s_nop 1
	v_cndmask_b32_e64 v90, v90, v92, s[40:41]
	v_cndmask_b32_e32 v92, 0, v252, vcc
	v_sub_f32_e32 v90, v90, v92
	v_add_f32_e32 v90, v91, v90
	v_fmamk_f32 v90, v90, 0xbd800000, v89
	s_waitcnt lgkmcnt(7)
	v_mul_f32_e32 v91, v80, v115
	v_fmac_f32_e32 v91, v79, v114
	v_fmac_f32_e32 v91, v83, v116
	v_fmac_f32_e32 v91, v84, v117
	ds_read_b128 v[114:117], v87 offset:384
	v_add_f32_e32 v91, v85, v91
	s_waitcnt lgkmcnt(7)
	v_mul_f32_e32 v93, v72, v119
	v_fmac_f32_e32 v93, v71, v118
	v_fmac_f32_e32 v93, v77, v120
	v_fmac_f32_e32 v93, v78, v121
	ds_read_b128 v[118:121], v87 offset:400
	v_add_f32_e32 v91, v91, v93
	s_waitcnt lgkmcnt(7)
	v_mul_f32_e32 v93, v75, v123
	v_fmac_f32_e32 v93, v73, v122
	v_fmac_f32_e32 v93, v81, v124
	v_fmac_f32_e32 v93, v82, v125
	ds_read_b128 v[122:125], v87 offset:416
	v_add_f32_e32 v91, v91, v93
	s_waitcnt lgkmcnt(7)
	v_mul_f32_e32 v93, v70, v127
	v_fmac_f32_e32 v93, v67, v126
	v_fmac_f32_e32 v93, v76, v128
	v_fmac_f32_e32 v93, v74, v129
	ds_read_b128 v[126:129], v87 offset:432
	v_add_f32_e32 v91, v91, v93
	v_max_f32_e64 v92, -v91, 0
	v_mul_f32_e64 v91, |v91|, s64
	v_exp_f32_e32 v91, v91
	s_nop 0
	v_add_f32_e32 v91, 1.0, v91
	v_cmp_gt_f32_e32 vcc, s65, v91
	s_nop 1
	v_cndmask_b32_e64 v93, 0, 32, vcc
	v_ldexp_f32 v91, v91, v93
	v_log_f32_e32 v91, v91
	s_nop 0
	v_mul_f32_e32 v93, 0x3f317217, v91
	v_fma_f32 v93, v91, s66, -v93
	v_fmac_f32_e32 v93, 0x3377d1cf, v91
	v_fmac_f32_e32 v93, 0x3f317217, v91
	v_cmp_lt_f32_e64 s[40:41], |v91|, s67
	s_nop 1
	v_cndmask_b32_e64 v91, v91, v93, s[40:41]
	v_cndmask_b32_e32 v93, 0, v252, vcc
	v_sub_f32_e32 v91, v91, v93
	v_add_f32_e32 v91, v92, v91
	v_fmamk_f32 v91, v91, 0xbd800000, v90
	s_waitcnt lgkmcnt(7)
	v_mul_f32_e32 v93, v80, v131
	v_fmac_f32_e32 v93, v79, v130
	v_fmac_f32_e32 v93, v83, v132
	v_fmac_f32_e32 v93, v84, v133
	ds_read_b128 v[130:133], v87 offset:448
	v_add_f32_e32 v96, v85, v93
	s_waitcnt lgkmcnt(7)
	v_mul_f32_e32 v93, v72, v135
	v_fmac_f32_e32 v93, v71, v134
	v_fmac_f32_e32 v93, v77, v136
	v_fmac_f32_e32 v93, v78, v137
	ds_read_b128 v[134:137], v87 offset:464
	v_add_f32_e32 v96, v96, v93
	s_waitcnt lgkmcnt(7)
	v_mul_f32_e32 v93, v75, v139
	v_fmac_f32_e32 v93, v73, v138
	v_fmac_f32_e32 v93, v81, v140
	v_fmac_f32_e32 v93, v82, v141
	ds_read_b128 v[138:141], v87 offset:480
	v_add_f32_e32 v96, v96, v93
	s_waitcnt lgkmcnt(7)
	v_mul_f32_e32 v93, v70, v143
	v_fmac_f32_e32 v93, v67, v142
	v_fmac_f32_e32 v93, v76, v144
	v_fmac_f32_e32 v93, v74, v145
	ds_read_b128 v[142:145], v87 offset:496
	v_add_f32_e32 v92, v96, v93
	v_max_f32_e64 v93, -v92, 0
	v_mul_f32_e64 v92, |v92|, s64
	v_exp_f32_e32 v92, v92
	s_nop 0
	v_add_f32_e32 v92, 1.0, v92
	v_cmp_gt_f32_e32 vcc, s65, v92
	s_nop 1
	v_cndmask_b32_e64 v94, 0, 32, vcc
	v_ldexp_f32 v92, v92, v94
	v_log_f32_e32 v92, v92
	s_nop 0
	v_mul_f32_e32 v94, 0x3f317217, v92
	v_fma_f32 v94, v92, s66, -v94
	v_fmac_f32_e32 v94, 0x3377d1cf, v92
	v_fmac_f32_e32 v94, 0x3f317217, v92
	v_cmp_lt_f32_e64 s[40:41], |v92|, s67
	s_nop 1
	v_cndmask_b32_e64 v92, v92, v94, s[40:41]
	v_cndmask_b32_e32 v94, 0, v252, vcc
	v_sub_f32_e32 v92, v92, v94
	v_add_f32_e32 v92, v93, v92
	v_fmamk_f32 v92, v92, 0xbd800000, v91
	s_waitcnt lgkmcnt(7)
; #define LAS __attribute__((address_space(3)))
; __device__ __forceinline__ void gla_logdecay(float (&b)[16], float& blast, const LAS float* glrs, const float (&wcol)[16], const float bias, int d, int g, LAS float* tot) {
;     float run = 0.f;
; #pragma unroll
;     for (int ii = 0; ii < 16; ++ii) { const LAS f32x4* gr = (const LAS f32x4*)(glrs + (16 * g + ii) * 16); float z = bias;
; #pragma unroll
;         for (int r4 = 0; r4 < 4; ++r4) { const f32x4 gv = gr[r4]; z += gv[0] * wcol[4 * r4] + gv[1] * wcol[4 * r4 + 1] + gv[2] * wcol[4 * r4 + 2] + gv[3] * wcol[4 * r4 + 3]; }
;         const float la = -(fmaxf(-z, 0.f) + __logf(1.0f + __expf(-fabsf(z)))) * (1.0f / 16.0f);
;         run += la; b[ii] = run; }
	v_mul_f32_e32 v93, v80, v115
	v_fmac_f32_e32 v93, v79, v114
	v_fmac_f32_e32 v93, v83, v116
	v_fmac_f32_e32 v93, v84, v117
	ds_read_b128 v[114:117], v87 offset:512
	v_add_f32_e32 v93, v85, v93
	s_waitcnt lgkmcnt(7)
	v_mul_f32_e32 v95, v72, v119
	v_fmac_f32_e32 v95, v71, v118
	v_fmac_f32_e32 v95, v77, v120
	v_fmac_f32_e32 v95, v78, v121
	ds_read_b128 v[118:121], v87 offset:528
	v_add_f32_e32 v93, v93, v95
	s_waitcnt lgkmcnt(7)
	v_mul_f32_e32 v95, v75, v123
	v_fmac_f32_e32 v95, v73, v122
	v_fmac_f32_e32 v95, v81, v124
	v_fmac_f32_e32 v95, v82, v125
	ds_read_b128 v[122:125], v87 offset:544
	v_add_f32_e32 v93, v93, v95
	s_waitcnt lgkmcnt(7)
	v_mul_f32_e32 v95, v70, v127
	v_fmac_f32_e32 v95, v67, v126
	v_fmac_f32_e32 v95, v76, v128
	v_fmac_f32_e32 v95, v74, v129
	ds_read_b128 v[126:129], v87 offset:560
	v_add_f32_e32 v93, v93, v95
	v_max_f32_e64 v94, -v93, 0
	v_mul_f32_e64 v93, |v93|, s64
	v_exp_f32_e32 v93, v93
	s_nop 0
	v_add_f32_e32 v93, 1.0, v93
	v_cmp_gt_f32_e32 vcc, s65, v93
	s_nop 1
	v_cndmask_b32_e64 v95, 0, 32, vcc
	v_ldexp_f32 v93, v93, v95
	v_log_f32_e32 v93, v93
	s_nop 0
	v_mul_f32_e32 v95, 0x3f317217, v93
	v_fma_f32 v95, v93, s66, -v95
	v_fmac_f32_e32 v95, 0x3377d1cf, v93
	v_fmac_f32_e32 v95, 0x3f317217, v93
	v_cmp_lt_f32_e64 s[40:41], |v93|, s67
	s_nop 1
	v_cndmask_b32_e64 v93, v93, v95, s[40:41]
	v_cndmask_b32_e32 v95, 0, v252, vcc
	v_sub_f32_e32 v93, v93, v95
	v_add_f32_e32 v93, v94, v93
	v_fmamk_f32 v93, v93, 0xbd800000, v92
	s_waitcnt lgkmcnt(7)
	v_mul_f32_e32 v95, v80, v131
	v_fmac_f32_e32 v95, v79, v130
	v_fmac_f32_e32 v95, v83, v132
	v_fmac_f32_e32 v95, v84, v133
	ds_read_b128 v[130:133], v87 offset:576
	v_add_f32_e32 v98, v85, v95
	s_waitcnt lgkmcnt(7)
	v_mul_f32_e32 v95, v72, v135
	v_fmac_f32_e32 v95, v71, v134
	v_fmac_f32_e32 v95, v77, v136
	v_fmac_f32_e32 v95, v78, v137
	ds_read_b128 v[134:137], v87 offset:592
	v_add_f32_e32 v98, v98, v95
	s_waitcnt lgkmcnt(7)
	v_mul_f32_e32 v95, v75, v139
	v_fmac_f32_e32 v95, v73, v138
	v_fmac_f32_e32 v95, v81, v140
	v_fmac_f32_e32 v95, v82, v141
	ds_read_b128 v[138:141], v87 offset:608
	v_add_f32_e32 v98, v98, v95
	s_waitcnt lgkmcnt(7)
	v_mul_f32_e32 v95, v70, v143
	v_fmac_f32_e32 v95, v67, v142
	v_fmac_f32_e32 v95, v76, v144
	v_fmac_f32_e32 v95, v74, v145
	ds_read_b128 v[142:145], v87 offset:624
	v_add_f32_e32 v94, v98, v95
	v_max_f32_e64 v95, -v94, 0
	v_mul_f32_e64 v94, |v94|, s64
	v_exp_f32_e32 v94, v94
	s_nop 0
	v_add_f32_e32 v94, 1.0, v94
	v_cmp_gt_f32_e32 vcc, s65, v94
	s_nop 1
	v_cndmask_b32_e64 v96, 0, 32, vcc
	v_ldexp_f32 v94, v94, v96
	v_log_f32_e32 v94, v94
	s_nop 0
	v_mul_f32_e32 v96, 0x3f317217, v94
	v_fma_f32 v96, v94, s66, -v96
	v_fmac_f32_e32 v96, 0x3377d1cf, v94
	v_fmac_f32_e32 v96, 0x3f317217, v94
	v_cmp_lt_f32_e64 s[40:41], |v94|, s67
	s_nop 1
	v_cndmask_b32_e64 v94, v94, v96, s[40:41]
	v_cndmask_b32_e32 v96, 0, v252, vcc
	v_sub_f32_e32 v94, v94, v96
	v_add_f32_e32 v94, v95, v94
	v_fmamk_f32 v94, v94, 0xbd800000, v93
	s_waitcnt lgkmcnt(7)
	v_mul_f32_e32 v95, v80, v115
	v_fmac_f32_e32 v95, v79, v114
	v_fmac_f32_e32 v95, v83, v116
	v_fmac_f32_e32 v95, v84, v117
	ds_read_b128 v[114:117], v87 offset:640
	v_add_f32_e32 v95, v85, v95
	s_waitcnt lgkmcnt(7)
	v_mul_f32_e32 v97, v72, v119
	v_fmac_f32_e32 v97, v71, v118
	v_fmac_f32_e32 v97, v77, v120
	v_fmac_f32_e32 v97, v78, v121
	ds_read_b128 v[118:121], v87 offset:656
	v_add_f32_e32 v95, v95, v97
	s_waitcnt lgkmcnt(7)
	v_mul_f32_e32 v97, v75, v123
	v_fmac_f32_e32 v97, v73, v122
	v_fmac_f32_e32 v97, v81, v124
	v_fmac_f32_e32 v97, v82, v125
	ds_read_b128 v[122:125], v87 offset:672
	v_add_f32_e32 v95, v95, v97
	s_waitcnt lgkmcnt(7)
	v_mul_f32_e32 v97, v70, v127
	v_fmac_f32_e32 v97, v67, v126
	v_fmac_f32_e32 v97, v76, v128
	v_fmac_f32_e32 v97, v74, v129
	ds_read_b128 v[126:129], v87 offset:688
	v_add_f32_e32 v95, v95, v97
	v_max_f32_e64 v96, -v95, 0
	v_mul_f32_e64 v95, |v95|, s64
	v_exp_f32_e32 v95, v95
	s_nop 0
	v_add_f32_e32 v95, 1.0, v95
	v_cmp_gt_f32_e32 vcc, s65, v95
	s_nop 1
	v_cndmask_b32_e64 v97, 0, 32, vcc
	v_ldexp_f32 v95, v95, v97
	v_log_f32_e32 v95, v95
	s_nop 0
	v_mul_f32_e32 v97, 0x3f317217, v95
	v_fma_f32 v97, v95, s66, -v97
	v_fmac_f32_e32 v97, 0x3377d1cf, v95
	v_fmac_f32_e32 v97, 0x3f317217, v95
	v_cmp_lt_f32_e64 s[40:41], |v95|, s67
	s_nop 1
	v_cndmask_b32_e64 v95, v95, v97, s[40:41]
	v_cndmask_b32_e32 v97, 0, v252, vcc
	v_sub_f32_e32 v95, v95, v97
	v_add_f32_e32 v95, v96, v95
	v_fmamk_f32 v95, v95, 0xbd800000, v94
	s_waitcnt lgkmcnt(7)
	v_mul_f32_e32 v97, v80, v131
	v_fmac_f32_e32 v97, v79, v130
	v_fmac_f32_e32 v97, v83, v132
	v_fmac_f32_e32 v97, v84, v133
	ds_read_b128 v[130:133], v87 offset:704
	v_add_f32_e32 v100, v85, v97
	s_waitcnt lgkmcnt(7)
	v_mul_f32_e32 v97, v72, v135
	v_fmac_f32_e32 v97, v71, v134
	v_fmac_f32_e32 v97, v77, v136
	v_fmac_f32_e32 v97, v78, v137
	ds_read_b128 v[134:137], v87 offset:720
	v_add_f32_e32 v100, v100, v97
	s_waitcnt lgkmcnt(7)
	v_mul_f32_e32 v97, v75, v139
	v_fmac_f32_e32 v97, v73, v138
	v_fmac_f32_e32 v97, v81, v140
	v_fmac_f32_e32 v97, v82, v141
	ds_read_b128 v[138:141], v87 offset:736
	v_add_f32_e32 v100, v100, v97
	s_waitcnt lgkmcnt(7)
	v_mul_f32_e32 v97, v70, v143
	v_fmac_f32_e32 v97, v67, v142
	v_fmac_f32_e32 v97, v76, v144
	v_fmac_f32_e32 v97, v74, v145
	ds_read_b128 v[142:145], v87 offset:752
	v_add_f32_e32 v96, v100, v97
	v_max_f32_e64 v97, -v96, 0
	v_mul_f32_e64 v96, |v96|, s64
	v_exp_f32_e32 v96, v96
	s_nop 0
	v_add_f32_e32 v96, 1.0, v96
	v_cmp_gt_f32_e32 vcc, s65, v96
	s_nop 1
	v_cndmask_b32_e64 v98, 0, 32, vcc
	v_ldexp_f32 v96, v96, v98
	v_log_f32_e32 v96, v96
	s_nop 0
	v_mul_f32_e32 v98, 0x3f317217, v96
	v_fma_f32 v98, v96, s66, -v98
	v_fmac_f32_e32 v98, 0x3377d1cf, v96
	v_fmac_f32_e32 v98, 0x3f317217, v96
	v_cmp_lt_f32_e64 s[40:41], |v96|, s67
	s_nop 1
	v_cndmask_b32_e64 v96, v96, v98, s[40:41]
	v_cndmask_b32_e32 v98, 0, v252, vcc
	v_sub_f32_e32 v96, v96, v98
	v_add_f32_e32 v96, v97, v96
	v_fmamk_f32 v96, v96, 0xbd800000, v95
	s_waitcnt lgkmcnt(7)
; #define LAS __attribute__((address_space(3)))
; __device__ __forceinline__ void gla_logdecay(float (&b)[16], float& blast, const LAS float* glrs, const float (&wcol)[16], const float bias, int d, int g, LAS float* tot) {
;     float run = 0.f;
; #pragma unroll
;     for (int ii = 0; ii < 16; ++ii) { const LAS f32x4* gr = (const LAS f32x4*)(glrs + (16 * g + ii) * 16); float z = bias;
; #pragma unroll
;         for (int r4 = 0; r4 < 4; ++r4) { const f32x4 gv = gr[r4]; z += gv[0] * wcol[4 * r4] + gv[1] * wcol[4 * r4 + 1] + gv[2] * wcol[4 * r4 + 2] + gv[3] * wcol[4 * r4 + 3]; }
;         const float la = -(fmaxf(-z, 0.f) + __logf(1.0f + __expf(-fabsf(z)))) * (1.0f / 16.0f);
;         run += la; b[ii] = run; }
	v_mul_f32_e32 v97, v80, v115
	v_fmac_f32_e32 v97, v79, v114
	v_fmac_f32_e32 v97, v83, v116
	v_fmac_f32_e32 v97, v84, v117
	ds_read_b128 v[114:117], v87 offset:768
	v_add_f32_e32 v97, v85, v97
	s_waitcnt lgkmcnt(7)
	v_mul_f32_e32 v99, v72, v119
	v_fmac_f32_e32 v99, v71, v118
	v_fmac_f32_e32 v99, v77, v120
	v_fmac_f32_e32 v99, v78, v121
	ds_read_b128 v[118:121], v87 offset:784
	v_add_f32_e32 v97, v97, v99
	s_waitcnt lgkmcnt(7)
	v_mul_f32_e32 v99, v75, v123
	v_fmac_f32_e32 v99, v73, v122
	v_fmac_f32_e32 v99, v81, v124
	v_fmac_f32_e32 v99, v82, v125
	ds_read_b128 v[122:125], v87 offset:800
	v_add_f32_e32 v97, v97, v99
	s_waitcnt lgkmcnt(7)
	v_mul_f32_e32 v99, v70, v127
	v_fmac_f32_e32 v99, v67, v126
	v_fmac_f32_e32 v99, v76, v128
	v_fmac_f32_e32 v99, v74, v129
	ds_read_b128 v[126:129], v87 offset:816
	v_add_f32_e32 v97, v97, v99
	v_max_f32_e64 v98, -v97, 0
	v_mul_f32_e64 v97, |v97|, s64
	v_exp_f32_e32 v97, v97
	s_nop 0
	v_add_f32_e32 v97, 1.0, v97
	v_cmp_gt_f32_e32 vcc, s65, v97
	s_nop 1
	v_cndmask_b32_e64 v99, 0, 32, vcc
	v_ldexp_f32 v97, v97, v99
	v_log_f32_e32 v97, v97
	s_nop 0
	v_mul_f32_e32 v99, 0x3f317217, v97
	v_fma_f32 v99, v97, s66, -v99
	v_fmac_f32_e32 v99, 0x3377d1cf, v97
	v_fmac_f32_e32 v99, 0x3f317217, v97
	v_cmp_lt_f32_e64 s[40:41], |v97|, s67
	s_nop 1
	v_cndmask_b32_e64 v97, v97, v99, s[40:41]
	v_cndmask_b32_e32 v99, 0, v252, vcc
	v_sub_f32_e32 v97, v97, v99
	v_add_f32_e32 v97, v98, v97
	v_fmamk_f32 v97, v97, 0xbd800000, v96
	s_waitcnt lgkmcnt(7)
	v_mul_f32_e32 v99, v80, v131
	v_fmac_f32_e32 v99, v79, v130
	v_fmac_f32_e32 v99, v83, v132
	v_fmac_f32_e32 v99, v84, v133
	ds_read_b128 v[130:133], v87 offset:832
	v_add_f32_e32 v102, v85, v99
	s_waitcnt lgkmcnt(7)
	v_mul_f32_e32 v99, v72, v135
	v_fmac_f32_e32 v99, v71, v134
	v_fmac_f32_e32 v99, v77, v136
	v_fmac_f32_e32 v99, v78, v137
	ds_read_b128 v[134:137], v87 offset:848
	v_add_f32_e32 v102, v102, v99
	s_waitcnt lgkmcnt(7)
	v_mul_f32_e32 v99, v75, v139
	v_fmac_f32_e32 v99, v73, v138
	v_fmac_f32_e32 v99, v81, v140
	v_fmac_f32_e32 v99, v82, v141
	ds_read_b128 v[138:141], v87 offset:864
	v_add_f32_e32 v102, v102, v99
	s_waitcnt lgkmcnt(7)
	v_mul_f32_e32 v99, v70, v143
	v_fmac_f32_e32 v99, v67, v142
	v_fmac_f32_e32 v99, v76, v144
	v_fmac_f32_e32 v99, v74, v145
	ds_read_b128 v[142:145], v87 offset:880
	v_add_f32_e32 v98, v102, v99
	v_max_f32_e64 v99, -v98, 0
	v_mul_f32_e64 v98, |v98|, s64
	v_exp_f32_e32 v98, v98
	s_nop 0
	v_add_f32_e32 v98, 1.0, v98
	v_cmp_gt_f32_e32 vcc, s65, v98
	s_nop 1
	v_cndmask_b32_e64 v100, 0, 32, vcc
	v_ldexp_f32 v98, v98, v100
	v_log_f32_e32 v98, v98
	s_nop 0
	v_mul_f32_e32 v100, 0x3f317217, v98
	v_fma_f32 v100, v98, s66, -v100
	v_fmac_f32_e32 v100, 0x3377d1cf, v98
	v_fmac_f32_e32 v100, 0x3f317217, v98
	v_cmp_lt_f32_e64 s[40:41], |v98|, s67
	s_nop 1
	v_cndmask_b32_e64 v98, v98, v100, s[40:41]
	v_cndmask_b32_e32 v100, 0, v252, vcc
	v_sub_f32_e32 v98, v98, v100
	v_add_f32_e32 v98, v99, v98
	v_fmamk_f32 v98, v98, 0xbd800000, v97
	s_waitcnt lgkmcnt(7)
	v_mul_f32_e32 v99, v80, v115
	v_fmac_f32_e32 v99, v79, v114
	v_fmac_f32_e32 v99, v83, v116
	v_fmac_f32_e32 v99, v84, v117
	ds_read_b128 v[114:117], v87 offset:896
	v_add_f32_e32 v99, v85, v99
	s_waitcnt lgkmcnt(7)
	v_mul_f32_e32 v101, v72, v119
	v_fmac_f32_e32 v101, v71, v118
	v_fmac_f32_e32 v101, v77, v120
	v_fmac_f32_e32 v101, v78, v121
	ds_read_b128 v[118:121], v87 offset:912
	v_add_f32_e32 v99, v99, v101
	s_waitcnt lgkmcnt(7)
	v_mul_f32_e32 v101, v75, v123
	v_fmac_f32_e32 v101, v73, v122
	v_fmac_f32_e32 v101, v81, v124
	v_fmac_f32_e32 v101, v82, v125
	ds_read_b128 v[122:125], v87 offset:928
	v_add_f32_e32 v99, v99, v101
	s_waitcnt lgkmcnt(7)
	v_mul_f32_e32 v101, v70, v127
	v_fmac_f32_e32 v101, v67, v126
	v_fmac_f32_e32 v101, v76, v128
	v_fmac_f32_e32 v101, v74, v129
	ds_read_b128 v[126:129], v87 offset:944
	v_add_f32_e32 v99, v99, v101
	v_max_f32_e64 v100, -v99, 0
	v_mul_f32_e64 v99, |v99|, s64
	v_exp_f32_e32 v99, v99
	s_nop 0
	v_add_f32_e32 v99, 1.0, v99
	v_cmp_gt_f32_e32 vcc, s65, v99
	s_nop 1
	v_cndmask_b32_e64 v101, 0, 32, vcc
	v_ldexp_f32 v99, v99, v101
	v_log_f32_e32 v99, v99
	s_nop 0
	v_mul_f32_e32 v101, 0x3f317217, v99
	v_fma_f32 v101, v99, s66, -v101
	v_fmac_f32_e32 v101, 0x3377d1cf, v99
	v_fmac_f32_e32 v101, 0x3f317217, v99
	v_cmp_lt_f32_e64 s[40:41], |v99|, s67
	s_nop 1
	v_cndmask_b32_e64 v99, v99, v101, s[40:41]
	v_cndmask_b32_e32 v101, 0, v252, vcc
	v_sub_f32_e32 v99, v99, v101
	v_add_f32_e32 v99, v100, v99
	v_fmamk_f32 v99, v99, 0xbd800000, v98
	s_waitcnt lgkmcnt(7)
	v_mul_f32_e32 v101, v80, v131
	v_fmac_f32_e32 v101, v79, v130
	v_fmac_f32_e32 v101, v83, v132
	v_fmac_f32_e32 v101, v84, v133
	ds_read_b128 v[130:133], v87 offset:960
	v_add_f32_e32 v104, v85, v101
	s_waitcnt lgkmcnt(7)
	v_mul_f32_e32 v101, v72, v135
	v_fmac_f32_e32 v101, v71, v134
	v_fmac_f32_e32 v101, v77, v136
	v_fmac_f32_e32 v101, v78, v137
	ds_read_b128 v[134:137], v87 offset:976
	v_add_f32_e32 v104, v104, v101
	s_waitcnt lgkmcnt(7)
	v_mul_f32_e32 v101, v75, v139
	v_fmac_f32_e32 v101, v73, v138
	v_fmac_f32_e32 v101, v81, v140
	v_fmac_f32_e32 v101, v82, v141
	ds_read_b128 v[138:141], v87 offset:992
	v_add_f32_e32 v104, v104, v101
	s_waitcnt lgkmcnt(7)
	v_mul_f32_e32 v101, v70, v143
	v_fmac_f32_e32 v101, v67, v142
	v_fmac_f32_e32 v101, v76, v144
	v_fmac_f32_e32 v101, v74, v145
	ds_read_b128 v[142:145], v87 offset:1008
	v_add_f32_e32 v100, v104, v101
	v_max_f32_e64 v101, -v100, 0
	v_mul_f32_e64 v100, |v100|, s64
	v_exp_f32_e32 v100, v100
	s_nop 0
	v_add_f32_e32 v100, 1.0, v100
	v_cmp_gt_f32_e32 vcc, s65, v100
	s_nop 1
	v_cndmask_b32_e64 v102, 0, 32, vcc
	v_ldexp_f32 v100, v100, v102
	v_log_f32_e32 v100, v100
	s_nop 0
	v_mul_f32_e32 v102, 0x3f317217, v100
	v_fma_f32 v102, v100, s66, -v102
	v_fmac_f32_e32 v102, 0x3377d1cf, v100
	v_fmac_f32_e32 v102, 0x3f317217, v100
	v_cmp_lt_f32_e64 s[40:41], |v100|, s67
	s_nop 1
	v_cndmask_b32_e64 v100, v100, v102, s[40:41]
	v_cndmask_b32_e32 v102, 0, v252, vcc
	v_sub_f32_e32 v100, v100, v102
	v_add_f32_e32 v100, v101, v100
	v_fmamk_f32 v100, v100, 0xbd800000, v99
	s_waitcnt lgkmcnt(7)
; #define LAS __attribute__((address_space(3)))
; __device__ __forceinline__ float bf2f(unsigned short h) { return __uint_as_float((unsigned)h << 16); }
; __device__ __forceinline__ unsigned short f2bf(float f) { return (unsigned short)(pg8::cvt_pk_bf16(f, 0.f) & 0xffffu); }
; __device__ __forceinline__ void gla_logdecay(float (&b)[16], float& blast, const LAS float* glrs, const float (&wcol)[16], const float bias, int d, int g, LAS float* tot) {
;     ...
;     for (int ii = 0; ii < 16; ++ii) { const LAS f32x4* gr = (const LAS f32x4*)(glrs + (16 * g + ii) * 16); float z = bias;
; #pragma unroll
;         for (int r4 = 0; r4 < 4; ++r4) { const f32x4 gv = gr[r4]; z += gv[0] * wcol[4 * r4] + gv[1] * wcol[4 * r4 + 1] + gv[2] * wcol[4 * r4 + 2] + gv[3] * wcol[4 * r4 + 3]; }
;         const float la = -(fmaxf(-z, 0.f) + __logf(1.0f + __expf(-fabsf(z)))) * (1.0f / 16.0f);
;         run += la; b[ii] = run; }
;     tot[g * 128 + d] = run;
;     __syncthreads();
;     float off = 0.f, all = 0.f;
; #pragma unroll
;     for (int gg = 0; gg < 4; ++gg) { const float tv = tot[gg * 128 + d]; all += tv; if (gg < g) off += tv; }
; #pragma unroll
;     for (int ii = 0; ii < 16; ++ii) b[ii] += off;
;     blast = all;
; }
; __device__ __forceinline__ void gla_stepC(LAS unsigned char* lds, int item, const bf16* proj, const bf16* vtg, const float* glr, const float* W2, const float* b2, const bf16* sT, const float* gout, bf16* mix) {
;     ...
;       for (int ii = 0; ii < 16; ++ii) { const float eb = __expf(b[ii]); const int o_ = (16 * g + ii) * QP + d;
;           QE[o_] = f2bf(bf2f(QE[o_]) * 0.08838834764831845f * eb);
;           KE[o_] = f2bf(bf2f(KE[o_]) * __builtin_amdgcn_rcpf(eb)); } }
	v_mul_f32_e32 v101, v80, v115
	v_fmac_f32_e32 v101, v79, v114
	v_fmac_f32_e32 v101, v83, v116
	v_fmac_f32_e32 v101, v84, v117
	v_add_f32_e32 v101, v85, v101
	s_waitcnt lgkmcnt(6)
	v_mul_f32_e32 v103, v72, v119
	v_fmac_f32_e32 v103, v71, v118
	v_fmac_f32_e32 v103, v77, v120
	v_fmac_f32_e32 v103, v78, v121
	v_add_f32_e32 v101, v101, v103
	s_waitcnt lgkmcnt(5)
	v_mul_f32_e32 v103, v75, v123
	v_fmac_f32_e32 v103, v73, v122
	v_fmac_f32_e32 v103, v81, v124
	v_fmac_f32_e32 v103, v82, v125
	v_add_f32_e32 v101, v101, v103
	s_waitcnt lgkmcnt(4)
	v_mul_f32_e32 v103, v70, v127
	v_fmac_f32_e32 v103, v67, v126
	v_fmac_f32_e32 v103, v76, v128
	v_fmac_f32_e32 v103, v74, v129
	v_add_f32_e32 v101, v101, v103
	v_max_f32_e64 v102, -v101, 0
	v_mul_f32_e64 v101, |v101|, s64
	v_exp_f32_e32 v101, v101
	s_nop 0
	v_add_f32_e32 v101, 1.0, v101
	v_cmp_gt_f32_e32 vcc, s65, v101
	s_nop 1
	v_cndmask_b32_e64 v103, 0, 32, vcc
	v_ldexp_f32 v101, v101, v103
	v_log_f32_e32 v101, v101
	s_nop 0
	v_mul_f32_e32 v103, 0x3f317217, v101
	v_fma_f32 v103, v101, s66, -v103
	v_fmac_f32_e32 v103, 0x3377d1cf, v101
	v_fmac_f32_e32 v103, 0x3f317217, v101
	v_cmp_lt_f32_e64 s[40:41], |v101|, s67
	s_nop 1
	v_cndmask_b32_e64 v101, v101, v103, s[40:41]
	v_cndmask_b32_e32 v103, 0, v252, vcc
	v_sub_f32_e32 v101, v101, v103
	v_add_f32_e32 v101, v102, v101
	v_fmamk_f32 v101, v101, 0xbd800000, v100
	s_waitcnt lgkmcnt(3)
	v_mul_f32_e32 v80, v80, v131
	v_fmac_f32_e32 v80, v79, v130
	v_fmac_f32_e32 v80, v83, v132
	v_fmac_f32_e32 v80, v84, v133
	v_add_f32_e32 v79, v85, v80
	s_waitcnt lgkmcnt(2)
	v_mul_f32_e32 v72, v72, v135
	v_fmac_f32_e32 v72, v71, v134
	v_fmac_f32_e32 v72, v77, v136
	v_fmac_f32_e32 v72, v78, v137
	v_add_f32_e32 v71, v79, v72
	s_waitcnt lgkmcnt(1)
	v_mul_f32_e32 v72, v75, v139
	v_fmac_f32_e32 v72, v73, v138
	v_fmac_f32_e32 v72, v81, v140
	v_fmac_f32_e32 v72, v82, v141
	v_add_f32_e32 v71, v71, v72
	s_waitcnt lgkmcnt(0)
	v_mul_f32_e32 v70, v70, v143
	v_fmac_f32_e32 v70, v67, v142
	v_fmac_f32_e32 v70, v76, v144
	v_fmac_f32_e32 v70, v74, v145
	v_add_f32_e32 v67, v71, v70
	v_max_f32_e64 v70, -v67, 0
	v_mul_f32_e64 v67, |v67|, s64
	v_exp_f32_e32 v67, v67
	s_nop 0
	v_add_f32_e32 v67, 1.0, v67
	v_cmp_gt_f32_e32 vcc, s65, v67
	s_nop 1
	v_cndmask_b32_e64 v71, 0, 32, vcc
	v_ldexp_f32 v67, v67, v71
	v_log_f32_e32 v67, v67
	s_nop 0
	v_mul_f32_e32 v71, 0x3f317217, v67
	v_fma_f32 v71, v67, s66, -v71
	v_fmac_f32_e32 v71, 0x3377d1cf, v67
	v_fmac_f32_e32 v71, 0x3f317217, v67
	v_cmp_lt_f32_e64 s[40:41], |v67|, s67
	s_nop 1
	v_cndmask_b32_e64 v67, v67, v71, s[40:41]
	v_cndmask_b32_e32 v71, 0, v252, vcc
	v_sub_f32_e32 v67, v67, v71
	v_add_f32_e32 v67, v70, v67
	v_lshl_add_u32 v70, v43, 2, 0
	v_add_u32_e32 v72, 0x14400, v70
	v_fmamk_f32 v67, v67, 0xbd800000, v101
	v_lshl_add_u32 v70, v41, 9, v72
	ds_write_b32 v70, v67
	s_waitcnt lgkmcnt(0)
	s_barrier
	ds_read2st64_b32 v[70:71], v72 offset1:2
	v_cmp_lt_i32_e32 vcc, 0, v41
	s_waitcnt lgkmcnt(0)
	v_add_f32_e32 v70, 0, v70
	v_cndmask_b32_e32 v70, 0, v70, vcc
	v_cmp_lt_i32_e32 vcc, 1, v41
	v_add_f32_e32 v71, v71, v70
	s_nop 0
	v_cndmask_b32_e32 v73, v70, v71, vcc
	ds_read2st64_b32 v[70:71], v72 offset0:4 offset1:6
	v_cmp_lt_i32_e32 vcc, 2, v41
	s_waitcnt lgkmcnt(0)
	v_add_f32_e32 v70, v70, v73
	v_cndmask_b32_e32 v70, v73, v70, vcc
	v_cmp_lt_i32_e32 vcc, 3, v41
	v_add_f32_e32 v71, v71, v70
	s_nop 0
	v_cndmask_b32_e32 v77, v70, v71, vcc
	v_add_f32_e32 v78, v86, v77
	v_add_f32_e32 v79, v88, v77
	v_add_f32_e32 v80, v89, v77
	v_add_f32_e32 v81, v90, v77
	v_add_f32_e32 v82, v91, v77
	v_add_f32_e32 v83, v92, v77
	v_add_f32_e32 v84, v93, v77
	v_add_f32_e32 v85, v94, v77
	v_add_f32_e32 v76, v95, v77
	v_add_f32_e32 v75, v96, v77
	v_add_f32_e32 v74, v97, v77
	v_add_f32_e32 v73, v98, v77
	v_add_f32_e32 v72, v99, v77
	v_add_f32_e32 v71, v100, v77
	v_add_f32_e32 v70, v101, v77
	v_add_f32_e32 v67, v77, v67
	v_mul_f32_e32 v77, 0x3fb8aa3b, v78
	v_mul_lo_u32 v78, v41, s0
	v_or_b32_e32 v43, v78, v43
	v_lshl_add_u32 v43, v43, 1, 0
	ds_read_u16 v78, v43
	v_exp_f32_e32 v77, v77
	v_mul_f32_e32 v76, 0x3fb8aa3b, v76
	v_exp_f32_e32 v76, v76
	v_mul_f32_e32 v75, 0x3fb8aa3b, v75
	s_waitcnt lgkmcnt(0)
	v_lshlrev_b32_e32 v78, 16, v78
	v_mul_f32_e32 v78, 0x3db504f3, v78
	v_mul_f32_e32 v78, v78, v77
	v_cvt_pk_bf16_f32 v78, v78, v153
	ds_write_b16 v43, v78
	ds_read_u16 v78, v43 offset:18432
	v_rcp_f32_e32 v77, v77
	v_exp_f32_e32 v75, v75
	v_mul_f32_e32 v74, 0x3fb8aa3b, v74
	v_exp_f32_e32 v74, v74
	s_waitcnt lgkmcnt(0)
	v_lshlrev_b32_e32 v78, 16, v78
	v_mul_f32_e32 v77, v77, v78
	v_cvt_pk_bf16_f32 v77, v77, v153
	ds_read_u16 v78, v43 offset:288
	ds_write_b16 v43, v77 offset:18432
	v_mul_f32_e32 v77, 0x3fb8aa3b, v79
	v_exp_f32_e32 v77, v77
	v_mul_f32_e32 v73, 0x3fb8aa3b, v73
	s_waitcnt lgkmcnt(1)
	v_lshlrev_b32_e32 v78, 16, v78
	v_mul_f32_e32 v78, 0x3db504f3, v78
	v_mul_f32_e32 v78, v77, v78
	v_cvt_pk_bf16_f32 v78, v78, v153
	ds_write_b16 v43, v78 offset:288
	ds_read_u16 v78, v43 offset:18720
	v_rcp_f32_e32 v77, v77
	v_exp_f32_e32 v73, v73
	v_mul_f32_e32 v72, 0x3fb8aa3b, v72
	v_exp_f32_e32 v72, v72
	s_waitcnt lgkmcnt(0)
	v_lshlrev_b32_e32 v78, 16, v78
	v_mul_f32_e32 v77, v77, v78
	v_cvt_pk_bf16_f32 v77, v77, v153
	ds_read_u16 v78, v43 offset:576
	ds_write_b16 v43, v77 offset:18720
	v_mul_f32_e32 v77, 0x3fb8aa3b, v80
	v_exp_f32_e32 v77, v77
	v_mul_f32_e32 v71, 0x3fb8aa3b, v71
	s_waitcnt lgkmcnt(1)
	v_lshlrev_b32_e32 v78, 16, v78
	v_mul_f32_e32 v78, 0x3db504f3, v78
	v_mul_f32_e32 v78, v77, v78
	v_cvt_pk_bf16_f32 v78, v78, v153
	ds_write_b16 v43, v78 offset:576
	ds_read_u16 v78, v43 offset:19008
	v_rcp_f32_e32 v77, v77
	v_exp_f32_e32 v71, v71
	v_mul_f32_e32 v70, 0x3fb8aa3b, v70
	v_exp_f32_e32 v70, v70
	s_waitcnt lgkmcnt(0)
; #define LAS __attribute__((address_space(3)))
; __device__ __forceinline__ float bf2f(unsigned short h) { return __uint_as_float((unsigned)h << 16); }
; __device__ __forceinline__ unsigned short f2bf(float f) { return (unsigned short)(pg8::cvt_pk_bf16(f, 0.f) & 0xffffu); }
; #define MMA16(X, Y, ACC) ACC = __builtin_amdgcn_mfma_f32_16x16x32_bf16((X), (Y), (ACC), 0, 0, 0)
; __device__ __forceinline__ void gla_stepC(LAS unsigned char* lds, int item, const bf16* proj, const bf16* vtg, const float* glr, const float* W2, const float* b2, const bf16* sT, const float* gout, bf16* mix) {
;     ...
;       for (int ii = 0; ii < 16; ++ii) { const float eb = __expf(b[ii]); const int o_ = (16 * g + ii) * QP + d;
;           QE[o_] = f2bf(bf2f(QE[o_]) * 0.08838834764831845f * eb);
;           KE[o_] = f2bf(bf2f(KE[o_]) * __builtin_amdgcn_rcpf(eb)); } }
;     __syncthreads();
;     { const int ib = w >> 1;
; #pragma unroll
;       for (int jj = 0; jj < 2; ++jj) { const int jb = 2 * (w & 1) + jj; f32x4 a = (f32x4){0.f, 0.f, 0.f, 0.f};
; #pragma unroll
;           for (int ks = 0; ks < 4; ++ks) { const bf16x8 kf = *(const LAS bf16x8*)(KE + (16 * jb + fr) * QP + 32 * ks + 8 * fq); const bf16x8 qf = *(const LAS bf16x8*)(QE + (16 * ib + fr) * QP + 32 * ks + 8 * fq); MMA16(kf, qf, a); }
;           const int i = 16 * ib + fr, j0 = 16 * jb + 4 * fq;
	v_lshlrev_b32_e32 v78, 16, v78
	v_mul_f32_e32 v77, v77, v78
	v_cvt_pk_bf16_f32 v77, v77, v153
	ds_read_u16 v78, v43 offset:864
	ds_write_b16 v43, v77 offset:19008
	v_mul_f32_e32 v77, 0x3fb8aa3b, v81
	v_exp_f32_e32 v77, v77
	v_mul_f32_e32 v67, 0x3fb8aa3b, v67
	s_waitcnt lgkmcnt(1)
	v_lshlrev_b32_e32 v78, 16, v78
	v_mul_f32_e32 v78, 0x3db504f3, v78
	v_mul_f32_e32 v78, v77, v78
	v_cvt_pk_bf16_f32 v78, v78, v153
	ds_write_b16 v43, v78 offset:864
	ds_read_u16 v78, v43 offset:19296
	v_rcp_f32_e32 v77, v77
	v_exp_f32_e32 v67, v67
	v_lshl_or_b32 v41, v41, 4, v47
	v_readlane_b32 s0, v255, 14
	s_waitcnt lgkmcnt(0)
	v_lshlrev_b32_e32 v78, 16, v78
	v_mul_f32_e32 v77, v77, v78
	v_cvt_pk_bf16_f32 v77, v77, v153
	ds_read_u16 v78, v43 offset:1152
	ds_write_b16 v43, v77 offset:19296
	v_mul_f32_e32 v77, 0x3fb8aa3b, v82
	v_exp_f32_e32 v77, v77
	s_waitcnt lgkmcnt(1)
	v_lshlrev_b32_e32 v78, 16, v78
	v_mul_f32_e32 v78, 0x3db504f3, v78
	v_mul_f32_e32 v78, v77, v78
	v_cvt_pk_bf16_f32 v78, v78, v153
	ds_write_b16 v43, v78 offset:1152
	ds_read_u16 v78, v43 offset:19584
	v_rcp_f32_e32 v77, v77
	s_waitcnt lgkmcnt(0)
	v_lshlrev_b32_e32 v78, 16, v78
	v_mul_f32_e32 v77, v77, v78
	v_cvt_pk_bf16_f32 v77, v77, v153
	ds_read_u16 v78, v43 offset:1440
	ds_write_b16 v43, v77 offset:19584
	v_mul_f32_e32 v77, 0x3fb8aa3b, v83
	v_exp_f32_e32 v77, v77
	s_waitcnt lgkmcnt(1)
	v_lshlrev_b32_e32 v78, 16, v78
	v_mul_f32_e32 v78, 0x3db504f3, v78
	v_mul_f32_e32 v78, v77, v78
	v_cvt_pk_bf16_f32 v78, v78, v153
	ds_write_b16 v43, v78 offset:1440
	ds_read_u16 v78, v43 offset:19872
	v_rcp_f32_e32 v77, v77
	s_waitcnt lgkmcnt(0)
	v_lshlrev_b32_e32 v78, 16, v78
	v_mul_f32_e32 v77, v77, v78
	v_cvt_pk_bf16_f32 v77, v77, v153
	ds_read_u16 v78, v43 offset:1728
	ds_write_b16 v43, v77 offset:19872
	v_mul_f32_e32 v77, 0x3fb8aa3b, v84
	v_exp_f32_e32 v77, v77
	s_waitcnt lgkmcnt(1)
	v_lshlrev_b32_e32 v78, 16, v78
	v_mul_f32_e32 v78, 0x3db504f3, v78
	v_mul_f32_e32 v78, v77, v78
	v_cvt_pk_bf16_f32 v78, v78, v153
	ds_write_b16 v43, v78 offset:1728
	ds_read_u16 v78, v43 offset:20160
	v_rcp_f32_e32 v77, v77
	s_waitcnt lgkmcnt(0)
	v_lshlrev_b32_e32 v78, 16, v78
	v_mul_f32_e32 v77, v77, v78
	v_cvt_pk_bf16_f32 v77, v77, v153
	ds_read_u16 v78, v43 offset:2016
	ds_write_b16 v43, v77 offset:20160
	v_mul_f32_e32 v77, 0x3fb8aa3b, v85
	v_exp_f32_e32 v77, v77
	s_waitcnt lgkmcnt(1)
	v_lshlrev_b32_e32 v78, 16, v78
	v_mul_f32_e32 v78, 0x3db504f3, v78
	v_mul_f32_e32 v78, v77, v78
	v_cvt_pk_bf16_f32 v78, v78, v153
	ds_write_b16 v43, v78 offset:2016
	ds_read_u16 v78, v43 offset:20448
	v_rcp_f32_e32 v77, v77
	s_waitcnt lgkmcnt(0)
	v_lshlrev_b32_e32 v78, 16, v78
	v_mul_f32_e32 v77, v77, v78
	v_cvt_pk_bf16_f32 v77, v77, v153
	ds_write_b16 v43, v77 offset:20448
	ds_read_u16 v77, v43 offset:2304
	s_waitcnt lgkmcnt(0)
	v_lshlrev_b32_e32 v77, 16, v77
	v_mul_f32_e32 v77, 0x3db504f3, v77
	v_mul_f32_e32 v77, v76, v77
	v_cvt_pk_bf16_f32 v77, v77, v153
	ds_write_b16 v43, v77 offset:2304
	ds_read_u16 v77, v43 offset:20736
	v_rcp_f32_e32 v76, v76
	s_waitcnt lgkmcnt(0)
	v_lshlrev_b32_e32 v77, 16, v77
	v_mul_f32_e32 v76, v76, v77
	v_cvt_pk_bf16_f32 v76, v76, v153
	ds_write_b16 v43, v76 offset:20736
	ds_read_u16 v76, v43 offset:2592
	s_waitcnt lgkmcnt(0)
	v_lshlrev_b32_e32 v76, 16, v76
	v_mul_f32_e32 v76, 0x3db504f3, v76
	v_mul_f32_e32 v76, v75, v76
	v_cvt_pk_bf16_f32 v76, v76, v153
	ds_write_b16 v43, v76 offset:2592
	ds_read_u16 v76, v43 offset:21024
	v_rcp_f32_e32 v75, v75
	s_waitcnt lgkmcnt(0)
	v_lshlrev_b32_e32 v76, 16, v76
	v_mul_f32_e32 v75, v75, v76
	v_cvt_pk_bf16_f32 v75, v75, v153
	ds_write_b16 v43, v75 offset:21024
	ds_read_u16 v75, v43 offset:2880
	s_waitcnt lgkmcnt(0)
	v_lshlrev_b32_e32 v75, 16, v75
	v_mul_f32_e32 v75, 0x3db504f3, v75
	v_mul_f32_e32 v75, v74, v75
	v_cvt_pk_bf16_f32 v75, v75, v153
	ds_write_b16 v43, v75 offset:2880
	ds_read_u16 v75, v43 offset:21312
	v_rcp_f32_e32 v74, v74
	s_waitcnt lgkmcnt(0)
	v_lshlrev_b32_e32 v75, 16, v75
	v_mul_f32_e32 v74, v74, v75
	v_cvt_pk_bf16_f32 v74, v74, v153
	ds_write_b16 v43, v74 offset:21312
	ds_read_u16 v74, v43 offset:3168
	s_waitcnt lgkmcnt(0)
	v_lshlrev_b32_e32 v74, 16, v74
	v_mul_f32_e32 v74, 0x3db504f3, v74
	v_mul_f32_e32 v74, v73, v74
	v_cvt_pk_bf16_f32 v74, v74, v153
	ds_write_b16 v43, v74 offset:3168
	ds_read_u16 v74, v43 offset:21600
	v_rcp_f32_e32 v73, v73
	s_waitcnt lgkmcnt(0)
	v_lshlrev_b32_e32 v74, 16, v74
	v_mul_f32_e32 v73, v73, v74
	v_cvt_pk_bf16_f32 v73, v73, v153
	ds_write_b16 v43, v73 offset:21600
	ds_read_u16 v73, v43 offset:3456
	s_waitcnt lgkmcnt(0)
	v_lshlrev_b32_e32 v73, 16, v73
	v_mul_f32_e32 v73, 0x3db504f3, v73
	v_mul_f32_e32 v73, v72, v73
	v_cvt_pk_bf16_f32 v73, v73, v153
	ds_write_b16 v43, v73 offset:3456
	ds_read_u16 v73, v43 offset:21888
	v_rcp_f32_e32 v72, v72
	s_waitcnt lgkmcnt(0)
	v_lshlrev_b32_e32 v73, 16, v73
	v_mul_f32_e32 v72, v72, v73
	v_cvt_pk_bf16_f32 v72, v72, v153
	ds_write_b16 v43, v72 offset:21888
	ds_read_u16 v72, v43 offset:3744
	s_waitcnt lgkmcnt(0)
	v_lshlrev_b32_e32 v72, 16, v72
	v_mul_f32_e32 v72, 0x3db504f3, v72
	v_mul_f32_e32 v72, v71, v72
	v_cvt_pk_bf16_f32 v72, v72, v153
	ds_write_b16 v43, v72 offset:3744
	ds_read_u16 v72, v43 offset:22176
	v_rcp_f32_e32 v71, v71
	s_waitcnt lgkmcnt(0)
	v_lshlrev_b32_e32 v72, 16, v72
	v_mul_f32_e32 v71, v71, v72
	v_cvt_pk_bf16_f32 v71, v71, v153
	ds_write_b16 v43, v71 offset:22176
	ds_read_u16 v71, v43 offset:4032
	s_waitcnt lgkmcnt(0)
	v_lshlrev_b32_e32 v71, 16, v71
	v_mul_f32_e32 v71, 0x3db504f3, v71
	v_mul_f32_e32 v71, v70, v71
	v_cvt_pk_bf16_f32 v71, v71, v153
	ds_write_b16 v43, v71 offset:4032
	ds_read_u16 v71, v43 offset:22464
	v_rcp_f32_e32 v70, v70
	s_waitcnt lgkmcnt(0)
	v_lshlrev_b32_e32 v71, 16, v71
	v_mul_f32_e32 v70, v70, v71
	v_cvt_pk_bf16_f32 v70, v70, v153
	ds_write_b16 v43, v70 offset:22464
	ds_read_u16 v70, v43 offset:4320
	s_waitcnt lgkmcnt(0)
	v_lshlrev_b32_e32 v70, 16, v70
	v_mul_f32_e32 v70, 0x3db504f3, v70
	v_mul_f32_e32 v70, v67, v70
	v_cvt_pk_bf16_f32 v70, v70, v153
	ds_write_b16 v43, v70 offset:4320
	ds_read_u16 v70, v43 offset:22752
	v_rcp_f32_e32 v67, v67
	s_waitcnt lgkmcnt(0)
	v_lshlrev_b32_e32 v70, 16, v70
	v_mul_f32_e32 v67, v67, v70
	v_cvt_pk_bf16_f32 v67, v67, v153
	ds_write_b16 v43, v67 offset:22752
	v_and_b32_e32 v43, 32, v42
	v_add_u32_e32 v42, 0, v152
	v_mad_u64_u32 v[82:83], s[14:15], v41, s94, v[42:43]
	v_or_b32_e32 v70, v43, v47
	v_mad_u32_u24 v83, v70, s94, v42
	s_waitcnt lgkmcnt(0)
	s_barrier
; #define LAS __attribute__((address_space(3)))
; __device__ __forceinline__ unsigned pk2(float lo, float hi) { return pg8::cvt_pk_bf16(lo, hi); }
; #define MMA16(X, Y, ACC) ACC = __builtin_amdgcn_mfma_f32_16x16x32_bf16((X), (Y), (ACC), 0, 0, 0)
; __device__ __forceinline__ void gla_stepC(LAS unsigned char* lds, int item, const bf16* proj, const bf16* vtg, const float* glr, const float* W2, const float* b2, const bf16* sT, const float* gout, bf16* mix) {
;     ...
;     { const int ib = w >> 1;
; #pragma unroll
;       for (int jj = 0; jj < 2; ++jj) { const int jb = 2 * (w & 1) + jj; f32x4 a = (f32x4){0.f, 0.f, 0.f, 0.f};
; #pragma unroll
;           for (int ks = 0; ks < 4; ++ks) { const bf16x8 kf = *(const LAS bf16x8*)(KE + (16 * jb + fr) * QP + 32 * ks + 8 * fq); const bf16x8 qf = *(const LAS bf16x8*)(QE + (16 * ib + fr) * QP + 32 * ks + 8 * fq); MMA16(kf, qf, a); }
;           const int i = 16 * ib + fr, j0 = 16 * jb + 4 * fq;
;           u32x2 ov; ov.x = pk2(j0 <= i ? a[0] : 0.f, j0 + 1 <= i ? a[1] : 0.f); ov.y = pk2(j0 + 2 <= i ? a[2] : 0.f, j0 + 3 <= i ? a[3] : 0.f);
;           *(LAS u32x2*)(AS + i * VP + j0) = ov; } }
;     __syncthreads();
	ds_read_b128 v[70:73], v83 offset:18432
	ds_read_b128 v[74:77], v82
	s_waitcnt lgkmcnt(0)
	v_mfma_f32_16x16x32_bf16 v[70:73], v[70:73], v[74:77], 0
	ds_read_b128 v[74:77], v83 offset:18496
	ds_read_b128 v[78:81], v82 offset:64
	v_mul_lo_u32 v67, v41, s16
	s_waitcnt lgkmcnt(0)
	v_mfma_f32_16x16x32_bf16 v[70:73], v[74:77], v[78:81], v[70:73]
	ds_read_b128 v[74:77], v83 offset:18560
	ds_read_b128 v[78:81], v82 offset:128
	s_waitcnt lgkmcnt(0)
	v_mfma_f32_16x16x32_bf16 v[70:73], v[74:77], v[78:81], v[70:73]
	ds_read_b128 v[74:77], v83 offset:18624
	ds_read_b128 v[78:81], v82 offset:192
	s_waitcnt lgkmcnt(0)
	v_mfma_f32_16x16x32_bf16 v[70:73], v[74:77], v[78:81], v[70:73]
	v_or_b32_e32 v74, v43, v63
	v_cmp_le_i32_e32 vcc, v74, v41
	v_or_b32_e32 v43, 16, v43
	s_nop 4
	v_cndmask_b32_e32 v70, 0, v70, vcc
	v_cmp_lt_i32_e32 vcc, v74, v41
	s_nop 1
	v_cndmask_b32_e32 v71, 0, v71, vcc
	v_cvt_pk_bf16_f32 v70, v70, v71
	v_or_b32_e32 v71, 2, v74
	v_cmp_le_i32_e32 vcc, v71, v41
	s_nop 1
	v_cndmask_b32_e32 v71, 0, v72, vcc
	v_or_b32_e32 v72, 3, v74
	v_cmp_le_i32_e32 vcc, v72, v41
	s_nop 1
	v_cndmask_b32_e32 v72, 0, v73, vcc
	v_cvt_pk_bf16_f32 v71, v71, v72
	v_lshlrev_b32_e32 v72, 1, v74
	v_add3_u32 v67, s0, v67, v72
	ds_write_b64 v67, v[70:71]
	v_or_b32_e32 v70, v43, v47
	v_mad_u32_u24 v83, v70, s94, v42
	ds_read_b128 v[70:73], v83 offset:18432
	ds_read_b128 v[74:77], v82
	s_waitcnt lgkmcnt(0)
	v_mfma_f32_16x16x32_bf16 v[70:73], v[70:73], v[74:77], 0
	ds_read_b128 v[74:77], v83 offset:18496
	ds_read_b128 v[78:81], v82 offset:64
	v_or_b32_e32 v43, v43, v63
	v_cmp_le_i32_e32 vcc, v43, v41
	s_waitcnt lgkmcnt(0)
	v_mfma_f32_16x16x32_bf16 v[70:73], v[74:77], v[78:81], v[70:73]
	ds_read_b128 v[74:77], v83 offset:18560
	ds_read_b128 v[78:81], v82 offset:128
	s_waitcnt lgkmcnt(0)
	v_mfma_f32_16x16x32_bf16 v[70:73], v[74:77], v[78:81], v[70:73]
	ds_read_b128 v[74:77], v83 offset:18624
	ds_read_b128 v[78:81], v82 offset:192
	s_waitcnt lgkmcnt(0)
	v_mfma_f32_16x16x32_bf16 v[70:73], v[74:77], v[78:81], v[70:73]
	s_nop 7
	v_cndmask_b32_e32 v70, 0, v70, vcc
	v_cmp_lt_i32_e32 vcc, v43, v41
	s_nop 1
	v_cndmask_b32_e32 v71, 0, v71, vcc
	v_cvt_pk_bf16_f32 v70, v70, v71
	v_or_b32_e32 v71, 2, v43
	v_cmp_le_i32_e32 vcc, v71, v41
	v_or_b32_e32 v43, 3, v43
	s_nop 0
	v_cndmask_b32_e32 v71, 0, v72, vcc
	v_cmp_le_i32_e32 vcc, v43, v41
	s_nop 1
	v_cndmask_b32_e32 v41, 0, v73, vcc
	v_cvt_pk_bf16_f32 v71, v71, v41
	v_mad_u64_u32 v[40:41], s[14:15], v40, s16, v[42:43]
	v_mul_u32_u24_e32 v41, 0x90, v47
	v_add3_u32 v41, s0, v152, v41
	ds_write_b64 v67, v[70:71] offset:32
	s_waitcnt lgkmcnt(0)
	s_barrier
; #define LAS __attribute__((address_space(3)))
; #define MMA16(X, Y, ACC) ACC = __builtin_amdgcn_mfma_f32_16x16x32_bf16((X), (Y), (ACC), 0, 0, 0)
; __device__ __forceinline__ void gla_stepC(LAS unsigned char* lds, int item, const bf16* proj, const bf16* vtg, const float* glr, const float* W2, const float* b2, const bf16* sT, const float* gout, bf16* mix) {
;     ...
;     f32x4 acc[2][4];
; #pragma unroll
;     for (int eb = 0; eb < 2; ++eb)
; #pragma unroll
;         for (int ib = 0; ib < 4; ++ib) acc[eb][ib] = (f32x4){0.f, 0.f, 0.f, 0.f};
; #pragma unroll
;     for (int ks = 0; ks < 2; ++ks) { bf16x8 vf[2];
; #pragma unroll
;         for (int eb = 0; eb < 2; ++eb) vf[eb] = *(const LAS bf16x8*)(VT + (32 * w + 16 * eb + fr) * VP + 32 * ks + 8 * fq);
; #pragma unroll
;         for (int ib = 0; ib < 4; ++ib) { const bf16x8 af = *(const LAS bf16x8*)(AS + (16 * ib + fr) * VP + 32 * ks + 8 * fq);
; #pragma unroll
;             for (int eb = 0; eb < 2; ++eb) MMA16(vf[eb], af, acc[eb][ib]); } }
; #pragma unroll
;     for (int ks = 0; ks < 4; ++ks) {
; #pragma unroll
;         for (int ib = 0; ib < 4; ++ib) { const bf16x8 qf = *(const LAS bf16x8*)(QE + (16 * ib + fr) * QP + 32 * ks + 8 * fq);
; #pragma unroll
;             for (int eb = 0; eb < 2; ++eb) MMA16(sfr[ks][eb], qf, acc[eb][ib]); } }
; #pragma unroll
;     for (int ib = 0; ib < 4; ++ib) { float q = 0.f;
; #pragma unroll
;         for (int eb = 0; eb < 2; ++eb) q += (acc[eb][ib][0] * acc[eb][ib][0] + acc[eb][ib][1] * acc[eb][ib][1]) + (acc[eb][ib][2] * acc[eb][ib][2] + acc[eb][ib][3] * acc[eb][ib][3]);
;         q += __shfl_xor(q, 16); q += __shfl_xor(q, 32);
;         if (fq == 0) red[w * 64 + 16 * ib + fr] = q; }
	ds_read_b128 v[70:73], v40 offset:36864
	ds_read_b128 v[74:77], v40 offset:39168
	ds_read_b128 v[78:81], v41
	ds_read_b128 v[86:89], v41 offset:2304
	ds_read_b128 v[94:97], v41 offset:4608
	ds_read_b128 v[102:105], v41 offset:6912
	s_waitcnt lgkmcnt(3)
	v_mfma_f32_16x16x32_bf16 v[82:85], v[70:73], v[78:81], 0
	v_mad_u32_u24 v67, v47, s94, v42
	v_cmp_lt_i32_e32 vcc, v179, v180
	v_readlane_b32 s0, v255, 18
	v_mfma_f32_16x16x32_bf16 v[78:81], v[74:77], v[78:81], 0
	s_waitcnt lgkmcnt(2)
	v_mfma_f32_16x16x32_bf16 v[90:93], v[70:73], v[86:89], 0
	v_mfma_f32_16x16x32_bf16 v[86:89], v[74:77], v[86:89], 0
	s_waitcnt lgkmcnt(1)
	v_mfma_f32_16x16x32_bf16 v[98:101], v[70:73], v[94:97], 0
	v_mfma_f32_16x16x32_bf16 v[94:97], v[74:77], v[94:97], 0
	s_waitcnt lgkmcnt(0)
	v_mfma_f32_16x16x32_bf16 v[70:73], v[70:73], v[102:105], 0
	v_mfma_f32_16x16x32_bf16 v[74:77], v[74:77], v[102:105], 0
	ds_read_b128 v[102:105], v40 offset:36928
	ds_read_b128 v[106:109], v40 offset:39232
	ds_read_b128 v[110:113], v41 offset:64
	s_waitcnt lgkmcnt(0)
	v_mfma_f32_16x16x32_bf16 v[82:85], v[102:105], v[110:113], v[82:85]
	v_mfma_f32_16x16x32_bf16 v[78:81], v[106:109], v[110:113], v[78:81]
	ds_read_b128 v[110:113], v41 offset:2368
	s_waitcnt lgkmcnt(0)
	v_mfma_f32_16x16x32_bf16 v[90:93], v[102:105], v[110:113], v[90:93]
	v_mfma_f32_16x16x32_bf16 v[86:89], v[106:109], v[110:113], v[86:89]
	ds_read_b128 v[110:113], v41 offset:4672
	s_waitcnt lgkmcnt(0)
	v_mfma_f32_16x16x32_bf16 v[98:101], v[102:105], v[110:113], v[98:101]
	v_mfma_f32_16x16x32_bf16 v[94:97], v[106:109], v[110:113], v[94:97]
	ds_read_b128 v[110:113], v41 offset:6976
	ds_read_b128 v[40:43], v67
	s_waitcnt lgkmcnt(0)
	v_mfma_f32_16x16x32_bf16 v[82:85], v[32:35], v[40:43], v[82:85]
	v_mfma_f32_16x16x32_bf16 v[40:43], v[36:39], v[40:43], v[78:81]
	s_nop 2
	ds_read_b128 v[78:81], v67 offset:4608
	s_waitcnt lgkmcnt(0)
	v_mfma_f32_16x16x32_bf16 v[90:93], v[32:35], v[78:81], v[90:93]
	v_mfma_f32_16x16x32_bf16 v[78:81], v[36:39], v[78:81], v[86:89]
	s_nop 2
	ds_read_b128 v[86:89], v67 offset:9216
	s_waitcnt lgkmcnt(0)
	v_mfma_f32_16x16x32_bf16 v[98:101], v[32:35], v[86:89], v[98:101]
	v_mfma_f32_16x16x32_bf16 v[86:89], v[36:39], v[86:89], v[94:97]
	s_nop 2
	ds_read_b128 v[94:97], v67 offset:13824
	v_mfma_f32_16x16x32_bf16 v[70:73], v[102:105], v[110:113], v[70:73]
	s_waitcnt lgkmcnt(0)
	v_mfma_f32_16x16x32_bf16 v[32:35], v[32:35], v[94:97], v[70:73]
	v_mfma_f32_16x16x32_bf16 v[74:77], v[106:109], v[110:113], v[74:77]
	s_nop 4
	ds_read_b128 v[70:73], v67 offset:64
	v_mfma_f32_16x16x32_bf16 v[36:39], v[36:39], v[94:97], v[74:77]
	s_waitcnt lgkmcnt(0)
	v_mfma_f32_16x16x32_bf16 v[74:77], v[24:27], v[70:73], v[82:85]
	v_mfma_f32_16x16x32_bf16 v[40:43], v[28:31], v[70:73], v[40:43]
	ds_read_b128 v[70:73], v67 offset:4672
	s_waitcnt lgkmcnt(0)
	v_mfma_f32_16x16x32_bf16 v[82:85], v[24:27], v[70:73], v[90:93]
	v_mfma_f32_16x16x32_bf16 v[70:73], v[28:31], v[70:73], v[78:81]
	s_nop 2
	ds_read_b128 v[78:81], v67 offset:9280
	s_waitcnt lgkmcnt(0)
	v_mfma_f32_16x16x32_bf16 v[90:93], v[24:27], v[78:81], v[98:101]
	v_mfma_f32_16x16x32_bf16 v[78:81], v[28:31], v[78:81], v[86:89]
	s_nop 2
	ds_read_b128 v[86:89], v67 offset:13888
	s_waitcnt lgkmcnt(0)
	v_mfma_f32_16x16x32_bf16 v[24:27], v[24:27], v[86:89], v[32:35]
	s_nop 2
	ds_read_b128 v[32:35], v67 offset:128
	v_mfma_f32_16x16x32_bf16 v[28:31], v[28:31], v[86:89], v[36:39]
	s_waitcnt lgkmcnt(0)
	v_mfma_f32_16x16x32_bf16 v[36:39], v[16:19], v[32:35], v[74:77]
	v_mfma_f32_16x16x32_bf16 v[32:35], v[20:23], v[32:35], v[40:43]
	s_nop 2
	ds_read_b128 v[40:43], v67 offset:4736
	s_waitcnt lgkmcnt(0)
	v_mfma_f32_16x16x32_bf16 v[74:77], v[16:19], v[40:43], v[82:85]
	v_mfma_f32_16x16x32_bf16 v[70:73], v[20:23], v[40:43], v[70:73]
	ds_read_b128 v[40:43], v67 offset:9344
	s_waitcnt lgkmcnt(0)
	v_mfma_f32_16x16x32_bf16 v[82:85], v[16:19], v[40:43], v[90:93]
	v_mfma_f32_16x16x32_bf16 v[78:81], v[20:23], v[40:43], v[78:81]
	ds_read_b128 v[40:43], v67 offset:13952
	s_waitcnt lgkmcnt(0)
	v_mfma_f32_16x16x32_bf16 v[86:89], v[20:23], v[40:43], v[28:31]
	ds_read_b128 v[20:23], v67 offset:192
	v_mfma_f32_16x16x32_bf16 v[16:19], v[16:19], v[40:43], v[24:27]
	s_waitcnt lgkmcnt(0)
	v_mfma_f32_16x16x32_bf16 v[40:43], v[8:11], v[20:23], v[36:39]
	v_mfma_f32_16x16x32_bf16 v[36:39], v[12:15], v[20:23], v[32:35]
	ds_read_b128 v[20:23], v67 offset:4800
	s_waitcnt lgkmcnt(0)
	v_mfma_f32_16x16x32_bf16 v[32:35], v[8:11], v[20:23], v[74:77]
	v_mfma_f32_16x16x32_bf16 v[28:31], v[12:15], v[20:23], v[70:73]
	ds_read_b128 v[20:23], v67 offset:9408
	s_nop 1
	ds_read_b128 v[70:73], v67 offset:14016
	s_waitcnt lgkmcnt(1)
	v_mfma_f32_16x16x32_bf16 v[24:27], v[8:11], v[20:23], v[82:85]
	v_mfma_f32_16x16x32_bf16 v[20:23], v[12:15], v[20:23], v[78:81]
	s_waitcnt lgkmcnt(0)
	v_mfma_f32_16x16x32_bf16 v[16:19], v[8:11], v[70:73], v[16:19]
	v_mfma_f32_16x16x32_bf16 v[8:11], v[12:15], v[70:73], v[86:89]
	v_cndmask_b32_e32 v12, v178, v179, vcc
	v_cmp_lt_i32_e32 vcc, v187, v180
	v_lshlrev_b32_e32 v13, 2, v12
	v_lshlrev_b32_e32 v15, 2, v47
	v_cndmask_b32_e32 v12, v178, v187, vcc
	v_lshlrev_b32_e32 v14, 2, v12
	v_and_b32_e32 v12, 0x3fffffc0, v55
	v_lshlrev_b32_e32 v12, 2, v12
	v_add3_u32 v12, s0, v12, v15
	v_mul_f32_e32 v15, v41, v41
	v_mul_f32_e32 v55, v43, v43
	v_fmac_f32_e32 v15, v40, v40
	v_fmac_f32_e32 v55, v42, v42
	v_cmp_eq_u32_e32 vcc, 0, v61
	v_add_f32_e32 v15, v15, v55
	v_mul_f32_e32 v55, v37, v37
	v_mul_f32_e32 v61, v39, v39
	v_fmac_f32_e32 v55, v36, v36
	v_fmac_f32_e32 v61, v38, v38
	v_add_f32_e32 v55, v55, v61
	v_add_f32_e32 v15, v15, v55
	ds_bpermute_b32 v55, v13, v15
	s_waitcnt lgkmcnt(0)
	v_add_f32_e32 v15, v15, v55
	ds_bpermute_b32 v55, v14, v15
	s_and_saveexec_b64 s[36:37], vcc
	s_cbranch_execz .LBB0_82
	s_waitcnt lgkmcnt(0)
	v_add_f32_e32 v15, v15, v55
	ds_write_b32 v12, v15

; __device__ __forceinline__ int tid_now() { int t = threadIdx.x; asm volatile("" : "+v"(t)); return t; }
; #define LAS __attribute__((address_space(3)))
; __device__ __forceinline__ void gla_stage_glr(LAS float* glrs, const float* glr, int R0, int tid) { if (tid < 256) *(LAS f32x4*)(glrs + tid * 4) = *(const f32x4*)(glr + (size_t)R0 * 16 + tid * 4); }
; __device__ __forceinline__ void gla_load_vt(LAS bf16* VT, const bf16* vsrc  ) {
;     const int tid = tid_now(), e = tid >> 1, hf = tid & 1;
;     const bf16* p = vsrc + (size_t)e * SEQ + 32 * hf;
; #pragma unroll
;     for (int q = 0; q < 4; ++q) *(LAS u32x4*)(VT + e * VP + 32 * hf + 8 * q) = *(const u32x4*)(p + 8 * q);
; __device__ __forceinline__ void gla_stepA(LAS unsigned char* lds, int item, const bf16* proj, const bf16* vtg, const float* glr, const float* W2, const float* b2, bf16* dST, float* decay) {
;     ...
;     const int d = tid & 127, g = tid >> 7;
;     float wcol[16];
; #pragma unroll
;     for (int r = 0; r < 16; ++r) wcol[r] = W2[r * 512 + hg * 128 + d];
;     const float wbias = b2[hg * 128 + d];
;     gla_stage_glr(glrs, glr, R0, tid);
;     gla_stage_raw(KR, proj + (size_t)R0 * PROJW + 3584 + hg * 128, PROJW, tid);
;     gla_load_vt(VT, vtg + (size_t)(bb * 4 + hg) * 256 * SEQ + n * 64);
;     __syncthreads();
.LBB0_149:
	v_readlane_b32 s0, v255, 16
	s_movk_i32 s15, 0x2000
	s_nop 0
	v_mov_b32_e32 v0, s0
	ds_read_b128 v[2:5], v0
	v_mov_b32_e32 v0, v176
	s_bfe_u32 s0, s46, 0x20005
	s_lshl_b32 s14, s0, 7
	v_and_b32_e32 v6, 0x7f, v0
	v_or_b32_e32 v1, s14, v6
	s_waitcnt lgkmcnt(0)
	v_readfirstlane_b32 s17, v3
	v_readfirstlane_b32 s16, v2
	v_lshlrev_b32_e32 v152, 2, v1
	v_readfirstlane_b32 s36, v4
	v_lshl_add_u64 v[20:21], s[16:17], 0, v[152:153]
	v_add_co_u32_e32 v2, vcc, s95, v20
	v_readfirstlane_b32 s37, v5
	s_nop 0
	v_addc_co_u32_e32 v3, vcc, 0, v21, vcc
	v_add_co_u32_e32 v4, vcc, s15, v20
	s_movk_i32 s15, 0x4000
	s_nop 0
	v_addc_co_u32_e32 v5, vcc, 0, v21, vcc
	v_add_co_u32_e32 v8, vcc, s97, v20
	global_load_dword v13, v152, s[16:17]
	global_load_dword v14, v152, s[16:17] offset:2048
	v_addc_co_u32_e32 v9, vcc, 0, v21, vcc
	v_add_co_u32_e32 v22, vcc, s15, v20
	s_movk_i32 s15, 0x5000
	s_nop 0
	v_addc_co_u32_e32 v23, vcc, 0, v21, vcc
	global_load_dword v17, v[4:5], off offset:-4096
	global_load_dword v18, v[2:3], off offset:2048
	s_nop 0
	global_load_dword v3, v[4:5], off
	s_nop 0
	global_load_dword v4, v[4:5], off offset:2048
	s_nop 0
	global_load_dword v11, v[22:23], off offset:-4096
	global_load_dword v12, v[8:9], off offset:2048
	global_load_dword v5, v[22:23], off
	s_nop 0
	global_load_dword v8, v[22:23], off offset:2048
	v_add_co_u32_e32 v22, vcc, s15, v20
	s_movk_i32 s15, 0x6000
	s_nop 0
	v_addc_co_u32_e32 v23, vcc, 0, v21, vcc
	v_add_co_u32_e32 v24, vcc, s15, v20
	s_ashr_i32 s16, s46, 7
	s_nop 0
	v_addc_co_u32_e32 v25, vcc, 0, v21, vcc
	v_add_co_u32_e32 v20, vcc, 0x7000, v20
	global_load_dword v15, v[24:25], off offset:-4096
	global_load_dword v16, v[22:23], off offset:2048
	global_load_dword v1, v[24:25], off
	global_load_dword v2, v[24:25], off offset:2048
	v_addc_co_u32_e32 v21, vcc, 0, v21, vcc
	global_load_dword v10, v[20:21], off
	global_load_dword v9, v[20:21], off offset:2048
	global_load_dword v19, v152, s[36:37]
	s_and_b32 s15, s26, 0x7c0
	s_lshl_b32 s17, s16, 11
	s_or_b32 s36, s17, s15
	s_movk_i32 s17, 0x100
	v_cmp_gt_i32_e32 vcc, s17, v0
	s_ashr_i32 s37, s36, 31
	s_and_saveexec_b64 s[40:41], vcc
	s_cbranch_execz .LBB0_151
	s_lshl_b64 s[22:23], s[36:37], 6
	v_lshlrev_b32_e32 v20, 2, v0
	s_add_u32 s22, s48, s22
	s_addc_u32 s23, s49, s23
	v_ashrrev_i32_e32 v21, 31, v20
	v_lshl_add_u64 v[20:21], v[20:21], 2, s[22:23]
	global_load_dwordx4 v[104:107], v[20:21], off
	v_lshl_add_u32 v124, v0, 4, 0
	v_add_u32_e32 v124, 0x12800, v124
.LBB0_151:
	s_or_b64 exec, exec, s[40:41]
	s_mul_i32 s22, s36, 0x3000
	s_mul_hi_i32 s17, s36, 0x3000
	s_add_u32 s22, s38, s22
	s_addc_u32 s17, s39, s17
	s_lshl_b32 s14, s14, 1
	s_add_u32 s14, s22, s14
	s_addc_u32 s17, s17, 0
	s_add_u32 s22, s14, 0x1c00
	s_addc_u32 s23, s17, 0
	v_ashrrev_i32_e32 v26, 3, v0
	v_mov_b64_e32 v[20:21], s[22:23]
	v_lshlrev_b32_e32 v22, 4, v0
	v_mad_i64_i32 v[20:21], s[22:23], v26, s97, v[20:21]
	v_and_b32_e32 v152, 0x70, v22
	v_lshl_add_u64 v[24:25], v[20:21], 0, v[152:153]
	global_load_dwordx4 v[108:111], v[24:25], off
	v_mul_lo_u32 v26, v26, s94
	v_add3_u32 v26, 0, v26, v152
	v_mov_b32_e32 v125, v26
	s_lshl_b32 s14, s16, 2
	s_or_b32 s16, s14, s0
	s_ashr_i32 s17, s16, 31
	s_lshl_b64 s[16:17], s[16:17], 20
	s_add_u32 s0, s71, s16
	s_addc_u32 s14, s80, s17
	s_lshl_b32 s15, s15, 1
	s_add_u32 s36, s0, s15
	s_addc_u32 s37, s14, 0
	s_movk_i32 s0, 0x90
	v_ashrrev_i32_e32 v7, 7, v0
	global_load_dwordx4 v[112:115], v[24:25], off offset:128
	v_mov_b32_e32 v24, v176
	s_nop 0
	v_ashrrev_i32_e32 v20, 1, v24
	v_ashrrev_i32_e32 v21, 31, v20
	v_lshlrev_b64 v[22:23], 12, v[20:21]
	v_lshlrev_b32_e32 v21, 6, v24
	v_lshl_add_u64 v[22:23], s[36:37], 0, v[22:23]
	v_and_b32_e32 v152, 64, v21
	v_lshl_add_u64 v[32:33], v[22:23], 0, v[152:153]
	v_mul_lo_u32 v20, v20, s0
	v_add3_u32 v36, 0, v20, v152
	global_load_dwordx4 v[20:23], v[32:33], off offset:48
	global_load_dwordx4 v[24:27], v[32:33], off offset:32
	global_load_dwordx4 v[28:31], v[32:33], off offset:16
	s_nop 0
	global_load_dwordx4 v[32:35], v[32:33], off
	s_mov_b32 s0, 0xbd800000
	v_cmp_gt_i32_e32 vcc, 0x100, v0
	s_waitcnt vmcnt(0)
	s_nop 0
	s_and_saveexec_b64 s[40:41], vcc
	ds_write_b128 v124, v[104:107]
	s_or_b64 exec, exec, s[40:41]
	ds_write_b128 v125, v[108:111] offset:18432
	ds_write_b128 v125, v[112:115] offset:18560
	ds_write_b128 v36, v[32:35] offset:36864
	ds_write_b128 v36, v[28:31] offset:36880
	ds_write_b128 v36, v[24:27] offset:36896
	ds_write_b128 v36, v[20:23] offset:36912
	v_lshl_add_u32 v20, v7, 10, 0
	v_add_u32_e32 v21, 0x12800, v20
	s_waitcnt lgkmcnt(0)
	s_barrier
; #define LAS __attribute__((address_space(3)))
; __device__ __forceinline__ void gla_logdecay(float (&b)[16], float& blast, const LAS float* glrs, const float (&wcol)[16], const float bias, int d, int g, LAS float* tot) {
;     float run = 0.f;
; #pragma unroll
;     for (int ii = 0; ii < 16; ++ii) { const LAS f32x4* gr = (const LAS f32x4*)(glrs + (16 * g + ii) * 16); float z = bias;
; #pragma unroll
;         for (int r4 = 0; r4 < 4; ++r4) { const f32x4 gv = gr[r4]; z += gv[0] * wcol[4 * r4] + gv[1] * wcol[4 * r4 + 1] + gv[2] * wcol[4 * r4 + 2] + gv[3] * wcol[4 * r4 + 3]; }
;         const float la = -(fmaxf(-z, 0.f) + __logf(1.0f + __expf(-fabsf(z)))) * (1.0f / 16.0f);
;         run += la; b[ii] = run; }
	ds_read_b128 v[114:117], v21
	ds_read_b128 v[118:121], v21 offset:16
	ds_read_b128 v[122:125], v21 offset:32
	ds_read_b128 v[126:129], v21 offset:48
	ds_read_b128 v[130:133], v21 offset:64
	ds_read_b128 v[134:137], v21 offset:80
	ds_read_b128 v[138:141], v21 offset:96
	ds_read_b128 v[142:145], v21 offset:112
	s_waitcnt lgkmcnt(7)
	v_mul_f32_e32 v20, v14, v115
	v_fmac_f32_e32 v20, v13, v114
	s_waitcnt lgkmcnt(6)
	v_mul_f32_e32 v22, v4, v119
	v_fmac_f32_e32 v20, v17, v116
	v_fmac_f32_e32 v22, v3, v118
	v_fmac_f32_e32 v20, v18, v117
	ds_read_b128 v[114:117], v21 offset:128
	v_fmac_f32_e32 v22, v11, v120
	v_add_f32_e32 v20, v19, v20
	v_fmac_f32_e32 v22, v12, v121
	ds_read_b128 v[118:121], v21 offset:144
	v_add_f32_e32 v20, v20, v22
	s_waitcnt lgkmcnt(7)
	v_mul_f32_e32 v22, v8, v123
	v_fmac_f32_e32 v22, v5, v122
	v_fmac_f32_e32 v22, v15, v124
	v_fmac_f32_e32 v22, v16, v125
	ds_read_b128 v[122:125], v21 offset:160
	v_add_f32_e32 v20, v20, v22
	s_waitcnt lgkmcnt(7)
	v_mul_f32_e32 v22, v2, v127
	v_fmac_f32_e32 v22, v1, v126
	v_fmac_f32_e32 v22, v10, v128
	v_fmac_f32_e32 v22, v9, v129
	ds_read_b128 v[126:129], v21 offset:176
	v_add_f32_e32 v20, v20, v22
	v_max_f32_e64 v22, -v20, 0
	v_mul_f32_e64 v20, |v20|, s64
	v_exp_f32_e32 v20, v20
	s_nop 0
	v_add_f32_e32 v20, 1.0, v20
	v_cmp_gt_f32_e32 vcc, s65, v20
	s_nop 1
	v_cndmask_b32_e64 v23, 0, 32, vcc
	v_ldexp_f32 v20, v20, v23
	v_log_f32_e32 v20, v20
	s_nop 0
	v_mul_f32_e32 v23, 0x3f317217, v20
	v_fma_f32 v23, v20, s66, -v23
	v_fmac_f32_e32 v23, 0x3377d1cf, v20
	v_fmac_f32_e32 v23, 0x3f317217, v20
	v_cmp_lt_f32_e64 s[40:41], |v20|, s67
	s_nop 1
	v_cndmask_b32_e64 v20, v20, v23, s[40:41]
	v_cndmask_b32_e32 v23, 0, v252, vcc
	v_sub_f32_e32 v20, v20, v23
	v_add_f32_e32 v20, v22, v20
	v_fma_f32 v20, v20, s0, 0
	s_movk_i32 s0, 0x80
	s_waitcnt lgkmcnt(7)
	v_mul_f32_e32 v23, v14, v131
	v_fmac_f32_e32 v23, v13, v130
	v_fmac_f32_e32 v23, v17, v132
	v_fmac_f32_e32 v23, v18, v133
	ds_read_b128 v[130:133], v21 offset:192
	v_add_f32_e32 v26, v19, v23
	s_waitcnt lgkmcnt(7)
	v_mul_f32_e32 v23, v4, v135
	v_fmac_f32_e32 v23, v3, v134
	v_fmac_f32_e32 v23, v11, v136
	v_fmac_f32_e32 v23, v12, v137
	ds_read_b128 v[134:137], v21 offset:208
	v_add_f32_e32 v26, v26, v23
	s_waitcnt lgkmcnt(7)
	v_mul_f32_e32 v23, v8, v139
	v_fmac_f32_e32 v23, v5, v138
	v_fmac_f32_e32 v23, v15, v140
	v_fmac_f32_e32 v23, v16, v141
	ds_read_b128 v[138:141], v21 offset:224
	v_add_f32_e32 v26, v26, v23
	s_waitcnt lgkmcnt(7)
	v_mul_f32_e32 v23, v2, v143
	v_fmac_f32_e32 v23, v1, v142
	v_fmac_f32_e32 v23, v10, v144
	v_fmac_f32_e32 v23, v9, v145
	ds_read_b128 v[142:145], v21 offset:240
	v_add_f32_e32 v22, v26, v23
	v_max_f32_e64 v23, -v22, 0
	v_mul_f32_e64 v22, |v22|, s64
	v_exp_f32_e32 v22, v22
	s_nop 0
	v_add_f32_e32 v22, 1.0, v22
	v_cmp_gt_f32_e32 vcc, s65, v22
	s_nop 1
	v_cndmask_b32_e64 v24, 0, 32, vcc
	v_ldexp_f32 v22, v22, v24
	v_log_f32_e32 v22, v22
	s_nop 0
	v_mul_f32_e32 v24, 0x3f317217, v22
	v_fma_f32 v24, v22, s66, -v24
	v_fmac_f32_e32 v24, 0x3377d1cf, v22
	v_fmac_f32_e32 v24, 0x3f317217, v22
	v_cmp_lt_f32_e64 s[40:41], |v22|, s67
	s_nop 1
	v_cndmask_b32_e64 v22, v22, v24, s[40:41]
	v_cndmask_b32_e32 v24, 0, v252, vcc
	v_sub_f32_e32 v22, v22, v24
	v_add_f32_e32 v22, v23, v22
	v_fmamk_f32 v22, v22, 0xbd800000, v20
	s_waitcnt lgkmcnt(7)
	v_mul_f32_e32 v23, v14, v115
	v_fmac_f32_e32 v23, v13, v114
	v_fmac_f32_e32 v23, v17, v116
	v_fmac_f32_e32 v23, v18, v117
	ds_read_b128 v[114:117], v21 offset:256
	v_add_f32_e32 v23, v19, v23
	s_waitcnt lgkmcnt(7)
	v_mul_f32_e32 v25, v4, v119
	v_fmac_f32_e32 v25, v3, v118
	v_fmac_f32_e32 v25, v11, v120
	v_fmac_f32_e32 v25, v12, v121
	ds_read_b128 v[118:121], v21 offset:272
	v_add_f32_e32 v23, v23, v25
	s_waitcnt lgkmcnt(7)
	v_mul_f32_e32 v25, v8, v123
	v_fmac_f32_e32 v25, v5, v122
	v_fmac_f32_e32 v25, v15, v124
	v_fmac_f32_e32 v25, v16, v125
	ds_read_b128 v[122:125], v21 offset:288
	v_add_f32_e32 v23, v23, v25
	s_waitcnt lgkmcnt(7)
	v_mul_f32_e32 v25, v2, v127
	v_fmac_f32_e32 v25, v1, v126
	v_fmac_f32_e32 v25, v10, v128
	v_fmac_f32_e32 v25, v9, v129
	ds_read_b128 v[126:129], v21 offset:304
	v_add_f32_e32 v23, v23, v25
	v_max_f32_e64 v24, -v23, 0
	v_mul_f32_e64 v23, |v23|, s64
	v_exp_f32_e32 v23, v23
	s_nop 0
	v_add_f32_e32 v23, 1.0, v23
	v_cmp_gt_f32_e32 vcc, s65, v23
	s_nop 1
	v_cndmask_b32_e64 v25, 0, 32, vcc
	v_ldexp_f32 v23, v23, v25
	v_log_f32_e32 v23, v23
	s_nop 0
	v_mul_f32_e32 v25, 0x3f317217, v23
	v_fma_f32 v25, v23, s66, -v25
	v_fmac_f32_e32 v25, 0x3377d1cf, v23
	v_fmac_f32_e32 v25, 0x3f317217, v23
	v_cmp_lt_f32_e64 s[40:41], |v23|, s67
	s_nop 1
	v_cndmask_b32_e64 v23, v23, v25, s[40:41]
	v_cndmask_b32_e32 v25, 0, v252, vcc
	v_sub_f32_e32 v23, v23, v25
	v_add_f32_e32 v23, v24, v23
	v_fmamk_f32 v23, v23, 0xbd800000, v22
	s_waitcnt lgkmcnt(7)
	v_mul_f32_e32 v25, v14, v131
	v_fmac_f32_e32 v25, v13, v130
	v_fmac_f32_e32 v25, v17, v132
	v_fmac_f32_e32 v25, v18, v133
	ds_read_b128 v[130:133], v21 offset:320
	v_add_f32_e32 v28, v19, v25
	s_waitcnt lgkmcnt(7)
	v_mul_f32_e32 v25, v4, v135
	v_fmac_f32_e32 v25, v3, v134
	v_fmac_f32_e32 v25, v11, v136
	v_fmac_f32_e32 v25, v12, v137
	ds_read_b128 v[134:137], v21 offset:336
	v_add_f32_e32 v28, v28, v25
	s_waitcnt lgkmcnt(7)
	v_mul_f32_e32 v25, v8, v139
	v_fmac_f32_e32 v25, v5, v138
	v_fmac_f32_e32 v25, v15, v140
	v_fmac_f32_e32 v25, v16, v141
	ds_read_b128 v[138:141], v21 offset:352
	v_add_f32_e32 v28, v28, v25
	s_waitcnt lgkmcnt(7)
; #define LAS __attribute__((address_space(3)))
; __device__ __forceinline__ void gla_logdecay(float (&b)[16], float& blast, const LAS float* glrs, const float (&wcol)[16], const float bias, int d, int g, LAS float* tot) {
;     float run = 0.f;
; #pragma unroll
;     for (int ii = 0; ii < 16; ++ii) { const LAS f32x4* gr = (const LAS f32x4*)(glrs + (16 * g + ii) * 16); float z = bias;
; #pragma unroll
;         for (int r4 = 0; r4 < 4; ++r4) { const f32x4 gv = gr[r4]; z += gv[0] * wcol[4 * r4] + gv[1] * wcol[4 * r4 + 1] + gv[2] * wcol[4 * r4 + 2] + gv[3] * wcol[4 * r4 + 3]; }
;         const float la = -(fmaxf(-z, 0.f) + __logf(1.0f + __expf(-fabsf(z)))) * (1.0f / 16.0f);
;         run += la; b[ii] = run; }
	v_mul_f32_e32 v25, v2, v143
	v_fmac_f32_e32 v25, v1, v142
	v_fmac_f32_e32 v25, v10, v144
	v_fmac_f32_e32 v25, v9, v145
	ds_read_b128 v[142:145], v21 offset:368
	v_add_f32_e32 v24, v28, v25
	v_max_f32_e64 v25, -v24, 0
	v_mul_f32_e64 v24, |v24|, s64
	v_exp_f32_e32 v24, v24
	s_nop 0
	v_add_f32_e32 v24, 1.0, v24
	v_cmp_gt_f32_e32 vcc, s65, v24
	s_nop 1
	v_cndmask_b32_e64 v26, 0, 32, vcc
	v_ldexp_f32 v24, v24, v26
	v_log_f32_e32 v24, v24
	s_nop 0
	v_mul_f32_e32 v26, 0x3f317217, v24
	v_fma_f32 v26, v24, s66, -v26
	v_fmac_f32_e32 v26, 0x3377d1cf, v24
	v_fmac_f32_e32 v26, 0x3f317217, v24
	v_cmp_lt_f32_e64 s[40:41], |v24|, s67
	s_nop 1
	v_cndmask_b32_e64 v24, v24, v26, s[40:41]
	v_cndmask_b32_e32 v26, 0, v252, vcc
	v_sub_f32_e32 v24, v24, v26
	v_add_f32_e32 v24, v25, v24
	v_fmamk_f32 v24, v24, 0xbd800000, v23
	s_waitcnt lgkmcnt(7)
	v_mul_f32_e32 v25, v14, v115
	v_fmac_f32_e32 v25, v13, v114
	v_fmac_f32_e32 v25, v17, v116
	v_fmac_f32_e32 v25, v18, v117
	ds_read_b128 v[114:117], v21 offset:384
	v_add_f32_e32 v25, v19, v25
	s_waitcnt lgkmcnt(7)
	v_mul_f32_e32 v27, v4, v119
	v_fmac_f32_e32 v27, v3, v118
	v_fmac_f32_e32 v27, v11, v120
	v_fmac_f32_e32 v27, v12, v121
	ds_read_b128 v[118:121], v21 offset:400
	v_add_f32_e32 v25, v25, v27
	s_waitcnt lgkmcnt(7)
	v_mul_f32_e32 v27, v8, v123
	v_fmac_f32_e32 v27, v5, v122
	v_fmac_f32_e32 v27, v15, v124
	v_fmac_f32_e32 v27, v16, v125
	ds_read_b128 v[122:125], v21 offset:416
	v_add_f32_e32 v25, v25, v27
	s_waitcnt lgkmcnt(7)
	v_mul_f32_e32 v27, v2, v127
	v_fmac_f32_e32 v27, v1, v126
	v_fmac_f32_e32 v27, v10, v128
	v_fmac_f32_e32 v27, v9, v129
	ds_read_b128 v[126:129], v21 offset:432
	v_add_f32_e32 v25, v25, v27
	v_max_f32_e64 v26, -v25, 0
	v_mul_f32_e64 v25, |v25|, s64
	v_exp_f32_e32 v25, v25
	s_nop 0
	v_add_f32_e32 v25, 1.0, v25
	v_cmp_gt_f32_e32 vcc, s65, v25
	s_nop 1
	v_cndmask_b32_e64 v27, 0, 32, vcc
	v_ldexp_f32 v25, v25, v27
	v_log_f32_e32 v25, v25
	s_nop 0
	v_mul_f32_e32 v27, 0x3f317217, v25
	v_fma_f32 v27, v25, s66, -v27
	v_fmac_f32_e32 v27, 0x3377d1cf, v25
	v_fmac_f32_e32 v27, 0x3f317217, v25
	v_cmp_lt_f32_e64 s[40:41], |v25|, s67
	s_nop 1
	v_cndmask_b32_e64 v25, v25, v27, s[40:41]
	v_cndmask_b32_e32 v27, 0, v252, vcc
	v_sub_f32_e32 v25, v25, v27
	v_add_f32_e32 v25, v26, v25
	v_fmamk_f32 v25, v25, 0xbd800000, v24
	s_waitcnt lgkmcnt(7)
	v_mul_f32_e32 v27, v14, v131
	v_fmac_f32_e32 v27, v13, v130
	v_fmac_f32_e32 v27, v17, v132
	v_fmac_f32_e32 v27, v18, v133
	ds_read_b128 v[130:133], v21 offset:448
	v_add_f32_e32 v30, v19, v27
	s_waitcnt lgkmcnt(7)
	v_mul_f32_e32 v27, v4, v135
	v_fmac_f32_e32 v27, v3, v134
	v_fmac_f32_e32 v27, v11, v136
	v_fmac_f32_e32 v27, v12, v137
	ds_read_b128 v[134:137], v21 offset:464
	v_add_f32_e32 v30, v30, v27
	s_waitcnt lgkmcnt(7)
	v_mul_f32_e32 v27, v8, v139
	v_fmac_f32_e32 v27, v5, v138
	v_fmac_f32_e32 v27, v15, v140
	v_fmac_f32_e32 v27, v16, v141
	ds_read_b128 v[138:141], v21 offset:480
	v_add_f32_e32 v30, v30, v27
	s_waitcnt lgkmcnt(7)
	v_mul_f32_e32 v27, v2, v143
	v_fmac_f32_e32 v27, v1, v142
	v_fmac_f32_e32 v27, v10, v144
	v_fmac_f32_e32 v27, v9, v145
	ds_read_b128 v[142:145], v21 offset:496
	v_add_f32_e32 v26, v30, v27
	v_max_f32_e64 v27, -v26, 0
	v_mul_f32_e64 v26, |v26|, s64
	v_exp_f32_e32 v26, v26
	s_nop 0
	v_add_f32_e32 v26, 1.0, v26
	v_cmp_gt_f32_e32 vcc, s65, v26
	s_nop 1
	v_cndmask_b32_e64 v28, 0, 32, vcc
	v_ldexp_f32 v26, v26, v28
	v_log_f32_e32 v26, v26
	s_nop 0
	v_mul_f32_e32 v28, 0x3f317217, v26
	v_fma_f32 v28, v26, s66, -v28
	v_fmac_f32_e32 v28, 0x3377d1cf, v26
	v_fmac_f32_e32 v28, 0x3f317217, v26
	v_cmp_lt_f32_e64 s[40:41], |v26|, s67
	s_nop 1
	v_cndmask_b32_e64 v26, v26, v28, s[40:41]
	v_cndmask_b32_e32 v28, 0, v252, vcc
	v_sub_f32_e32 v26, v26, v28
	v_add_f32_e32 v26, v27, v26
	v_fmamk_f32 v26, v26, 0xbd800000, v25
	s_waitcnt lgkmcnt(7)
	v_mul_f32_e32 v27, v14, v115
	v_fmac_f32_e32 v27, v13, v114
	v_fmac_f32_e32 v27, v17, v116
	v_fmac_f32_e32 v27, v18, v117
	ds_read_b128 v[114:117], v21 offset:512
	v_add_f32_e32 v27, v19, v27
	s_waitcnt lgkmcnt(7)
	v_mul_f32_e32 v29, v4, v119
	v_fmac_f32_e32 v29, v3, v118
	v_fmac_f32_e32 v29, v11, v120
	v_fmac_f32_e32 v29, v12, v121
	ds_read_b128 v[118:121], v21 offset:528
	v_add_f32_e32 v27, v27, v29
	s_waitcnt lgkmcnt(7)
	v_mul_f32_e32 v29, v8, v123
	v_fmac_f32_e32 v29, v5, v122
	v_fmac_f32_e32 v29, v15, v124
	v_fmac_f32_e32 v29, v16, v125
	ds_read_b128 v[122:125], v21 offset:544
	v_add_f32_e32 v27, v27, v29
	s_waitcnt lgkmcnt(7)
	v_mul_f32_e32 v29, v2, v127
	v_fmac_f32_e32 v29, v1, v126
	v_fmac_f32_e32 v29, v10, v128
	v_fmac_f32_e32 v29, v9, v129
	ds_read_b128 v[126:129], v21 offset:560
	v_add_f32_e32 v27, v27, v29
	v_max_f32_e64 v28, -v27, 0
	v_mul_f32_e64 v27, |v27|, s64
	v_exp_f32_e32 v27, v27
	s_nop 0
	v_add_f32_e32 v27, 1.0, v27
	v_cmp_gt_f32_e32 vcc, s65, v27
	s_nop 1
	v_cndmask_b32_e64 v29, 0, 32, vcc
	v_ldexp_f32 v27, v27, v29
	v_log_f32_e32 v27, v27
	s_nop 0
	v_mul_f32_e32 v29, 0x3f317217, v27
	v_fma_f32 v29, v27, s66, -v29
	v_fmac_f32_e32 v29, 0x3377d1cf, v27
	v_fmac_f32_e32 v29, 0x3f317217, v27
	v_cmp_lt_f32_e64 s[40:41], |v27|, s67
	s_nop 1
	v_cndmask_b32_e64 v27, v27, v29, s[40:41]
	v_cndmask_b32_e32 v29, 0, v252, vcc
	v_sub_f32_e32 v27, v27, v29
	v_add_f32_e32 v27, v28, v27
	v_fmamk_f32 v27, v27, 0xbd800000, v26
	s_waitcnt lgkmcnt(7)
	v_mul_f32_e32 v29, v14, v131
	v_fmac_f32_e32 v29, v13, v130
	v_fmac_f32_e32 v29, v17, v132
	v_fmac_f32_e32 v29, v18, v133
	ds_read_b128 v[130:133], v21 offset:576
	v_add_f32_e32 v32, v19, v29
	s_waitcnt lgkmcnt(7)
	v_mul_f32_e32 v29, v4, v135
	v_fmac_f32_e32 v29, v3, v134
	v_fmac_f32_e32 v29, v11, v136
	v_fmac_f32_e32 v29, v12, v137
	ds_read_b128 v[134:137], v21 offset:592
	v_add_f32_e32 v32, v32, v29
	s_waitcnt lgkmcnt(7)
; #define LAS __attribute__((address_space(3)))
; __device__ __forceinline__ void gla_logdecay(float (&b)[16], float& blast, const LAS float* glrs, const float (&wcol)[16], const float bias, int d, int g, LAS float* tot) {
;     float run = 0.f;
; #pragma unroll
;     for (int ii = 0; ii < 16; ++ii) { const LAS f32x4* gr = (const LAS f32x4*)(glrs + (16 * g + ii) * 16); float z = bias;
; #pragma unroll
;         for (int r4 = 0; r4 < 4; ++r4) { const f32x4 gv = gr[r4]; z += gv[0] * wcol[4 * r4] + gv[1] * wcol[4 * r4 + 1] + gv[2] * wcol[4 * r4 + 2] + gv[3] * wcol[4 * r4 + 3]; }
;         const float la = -(fmaxf(-z, 0.f) + __logf(1.0f + __expf(-fabsf(z)))) * (1.0f / 16.0f);
;         run += la; b[ii] = run; }
	v_mul_f32_e32 v29, v8, v139
	v_fmac_f32_e32 v29, v5, v138
	v_fmac_f32_e32 v29, v15, v140
	v_fmac_f32_e32 v29, v16, v141
	ds_read_b128 v[138:141], v21 offset:608
	v_add_f32_e32 v32, v32, v29
	s_waitcnt lgkmcnt(7)
	v_mul_f32_e32 v29, v2, v143
	v_fmac_f32_e32 v29, v1, v142
	v_fmac_f32_e32 v29, v10, v144
	v_fmac_f32_e32 v29, v9, v145
	ds_read_b128 v[142:145], v21 offset:624
	v_add_f32_e32 v28, v32, v29
	v_max_f32_e64 v29, -v28, 0
	v_mul_f32_e64 v28, |v28|, s64
	v_exp_f32_e32 v28, v28
	s_nop 0
	v_add_f32_e32 v28, 1.0, v28
	v_cmp_gt_f32_e32 vcc, s65, v28
	s_nop 1
	v_cndmask_b32_e64 v30, 0, 32, vcc
	v_ldexp_f32 v28, v28, v30
	v_log_f32_e32 v28, v28
	s_nop 0
	v_mul_f32_e32 v30, 0x3f317217, v28
	v_fma_f32 v30, v28, s66, -v30
	v_fmac_f32_e32 v30, 0x3377d1cf, v28
	v_fmac_f32_e32 v30, 0x3f317217, v28
	v_cmp_lt_f32_e64 s[40:41], |v28|, s67
	s_nop 1
	v_cndmask_b32_e64 v28, v28, v30, s[40:41]
	v_cndmask_b32_e32 v30, 0, v252, vcc
	v_sub_f32_e32 v28, v28, v30
	v_add_f32_e32 v28, v29, v28
	v_fmamk_f32 v28, v28, 0xbd800000, v27
	s_waitcnt lgkmcnt(7)
	v_mul_f32_e32 v29, v14, v115
	v_fmac_f32_e32 v29, v13, v114
	v_fmac_f32_e32 v29, v17, v116
	v_fmac_f32_e32 v29, v18, v117
	ds_read_b128 v[114:117], v21 offset:640
	v_add_f32_e32 v29, v19, v29
	s_waitcnt lgkmcnt(7)
	v_mul_f32_e32 v31, v4, v119
	v_fmac_f32_e32 v31, v3, v118
	v_fmac_f32_e32 v31, v11, v120
	v_fmac_f32_e32 v31, v12, v121
	ds_read_b128 v[118:121], v21 offset:656
	v_add_f32_e32 v29, v29, v31
	s_waitcnt lgkmcnt(7)
	v_mul_f32_e32 v31, v8, v123
	v_fmac_f32_e32 v31, v5, v122
	v_fmac_f32_e32 v31, v15, v124
	v_fmac_f32_e32 v31, v16, v125
	ds_read_b128 v[122:125], v21 offset:672
	v_add_f32_e32 v29, v29, v31
	s_waitcnt lgkmcnt(7)
	v_mul_f32_e32 v31, v2, v127
	v_fmac_f32_e32 v31, v1, v126
	v_fmac_f32_e32 v31, v10, v128
	v_fmac_f32_e32 v31, v9, v129
	ds_read_b128 v[126:129], v21 offset:688
	v_add_f32_e32 v29, v29, v31
	v_max_f32_e64 v30, -v29, 0
	v_mul_f32_e64 v29, |v29|, s64
	v_exp_f32_e32 v29, v29
	s_nop 0
	v_add_f32_e32 v29, 1.0, v29
	v_cmp_gt_f32_e32 vcc, s65, v29
	s_nop 1
	v_cndmask_b32_e64 v31, 0, 32, vcc
	v_ldexp_f32 v29, v29, v31
	v_log_f32_e32 v29, v29
	s_nop 0
	v_mul_f32_e32 v31, 0x3f317217, v29
	v_fma_f32 v31, v29, s66, -v31
	v_fmac_f32_e32 v31, 0x3377d1cf, v29
	v_fmac_f32_e32 v31, 0x3f317217, v29
	v_cmp_lt_f32_e64 s[40:41], |v29|, s67
	s_nop 1
	v_cndmask_b32_e64 v29, v29, v31, s[40:41]
	v_cndmask_b32_e32 v31, 0, v252, vcc
	v_sub_f32_e32 v29, v29, v31
	v_add_f32_e32 v29, v30, v29
	v_fmamk_f32 v29, v29, 0xbd800000, v28
	s_waitcnt lgkmcnt(7)
	v_mul_f32_e32 v31, v14, v131
	v_fmac_f32_e32 v31, v13, v130
	v_fmac_f32_e32 v31, v17, v132
	v_fmac_f32_e32 v31, v18, v133
	ds_read_b128 v[130:133], v21 offset:704
	v_add_f32_e32 v34, v19, v31
	s_waitcnt lgkmcnt(7)
	v_mul_f32_e32 v31, v4, v135
	v_fmac_f32_e32 v31, v3, v134
	v_fmac_f32_e32 v31, v11, v136
	v_fmac_f32_e32 v31, v12, v137
	ds_read_b128 v[134:137], v21 offset:720
	v_add_f32_e32 v34, v34, v31
	s_waitcnt lgkmcnt(7)
	v_mul_f32_e32 v31, v8, v139
	v_fmac_f32_e32 v31, v5, v138
	v_fmac_f32_e32 v31, v15, v140
	v_fmac_f32_e32 v31, v16, v141
	ds_read_b128 v[138:141], v21 offset:736
	v_add_f32_e32 v34, v34, v31
	s_waitcnt lgkmcnt(7)
	v_mul_f32_e32 v31, v2, v143
	v_fmac_f32_e32 v31, v1, v142
	v_fmac_f32_e32 v31, v10, v144
	v_fmac_f32_e32 v31, v9, v145
	ds_read_b128 v[142:145], v21 offset:752
	v_add_f32_e32 v30, v34, v31
	v_max_f32_e64 v31, -v30, 0
	v_mul_f32_e64 v30, |v30|, s64
	v_exp_f32_e32 v30, v30
	s_nop 0
	v_add_f32_e32 v30, 1.0, v30
	v_cmp_gt_f32_e32 vcc, s65, v30
	s_nop 1
	v_cndmask_b32_e64 v32, 0, 32, vcc
	v_ldexp_f32 v30, v30, v32
	v_log_f32_e32 v30, v30
	s_nop 0
	v_mul_f32_e32 v32, 0x3f317217, v30
	v_fma_f32 v32, v30, s66, -v32
	v_fmac_f32_e32 v32, 0x3377d1cf, v30
	v_fmac_f32_e32 v32, 0x3f317217, v30
	v_cmp_lt_f32_e64 s[40:41], |v30|, s67
	s_nop 1
	v_cndmask_b32_e64 v30, v30, v32, s[40:41]
	v_cndmask_b32_e32 v32, 0, v252, vcc
	v_sub_f32_e32 v30, v30, v32
	v_add_f32_e32 v30, v31, v30
	v_fmamk_f32 v30, v30, 0xbd800000, v29
	s_waitcnt lgkmcnt(7)
	v_mul_f32_e32 v31, v14, v115
	v_fmac_f32_e32 v31, v13, v114
	v_fmac_f32_e32 v31, v17, v116
	v_fmac_f32_e32 v31, v18, v117
	ds_read_b128 v[114:117], v21 offset:768
	v_add_f32_e32 v31, v19, v31
	s_waitcnt lgkmcnt(7)
	v_mul_f32_e32 v33, v4, v119
	v_fmac_f32_e32 v33, v3, v118
	v_fmac_f32_e32 v33, v11, v120
	v_fmac_f32_e32 v33, v12, v121
	ds_read_b128 v[118:121], v21 offset:784
	v_add_f32_e32 v31, v31, v33
	s_waitcnt lgkmcnt(7)
	v_mul_f32_e32 v33, v8, v123
	v_fmac_f32_e32 v33, v5, v122
	v_fmac_f32_e32 v33, v15, v124
	v_fmac_f32_e32 v33, v16, v125
	ds_read_b128 v[122:125], v21 offset:800
	v_add_f32_e32 v31, v31, v33
	s_waitcnt lgkmcnt(7)
	v_mul_f32_e32 v33, v2, v127
	v_fmac_f32_e32 v33, v1, v126
	v_fmac_f32_e32 v33, v10, v128
	v_fmac_f32_e32 v33, v9, v129
	ds_read_b128 v[126:129], v21 offset:816
	v_add_f32_e32 v31, v31, v33
	v_max_f32_e64 v32, -v31, 0
	v_mul_f32_e64 v31, |v31|, s64
	v_exp_f32_e32 v31, v31
	s_nop 0
	v_add_f32_e32 v31, 1.0, v31
	v_cmp_gt_f32_e32 vcc, s65, v31
	s_nop 1
	v_cndmask_b32_e64 v33, 0, 32, vcc
	v_ldexp_f32 v31, v31, v33
	v_log_f32_e32 v31, v31
	s_nop 0
	v_mul_f32_e32 v33, 0x3f317217, v31
	v_fma_f32 v33, v31, s66, -v33
	v_fmac_f32_e32 v33, 0x3377d1cf, v31
	v_fmac_f32_e32 v33, 0x3f317217, v31
	v_cmp_lt_f32_e64 s[40:41], |v31|, s67
	s_nop 1
	v_cndmask_b32_e64 v31, v31, v33, s[40:41]
	v_cndmask_b32_e32 v33, 0, v252, vcc
	v_sub_f32_e32 v31, v31, v33
	v_add_f32_e32 v31, v32, v31
	v_fmamk_f32 v31, v31, 0xbd800000, v30
	s_waitcnt lgkmcnt(7)
	v_mul_f32_e32 v33, v14, v131
	v_fmac_f32_e32 v33, v13, v130
	v_fmac_f32_e32 v33, v17, v132
	v_fmac_f32_e32 v33, v18, v133
	ds_read_b128 v[130:133], v21 offset:832
	v_add_f32_e32 v36, v19, v33
	s_waitcnt lgkmcnt(7)
; #define LAS __attribute__((address_space(3)))
; __device__ __forceinline__ void gla_logdecay(float (&b)[16], float& blast, const LAS float* glrs, const float (&wcol)[16], const float bias, int d, int g, LAS float* tot) {
;     float run = 0.f;
; #pragma unroll
;     for (int ii = 0; ii < 16; ++ii) { const LAS f32x4* gr = (const LAS f32x4*)(glrs + (16 * g + ii) * 16); float z = bias;
; #pragma unroll
;         for (int r4 = 0; r4 < 4; ++r4) { const f32x4 gv = gr[r4]; z += gv[0] * wcol[4 * r4] + gv[1] * wcol[4 * r4 + 1] + gv[2] * wcol[4 * r4 + 2] + gv[3] * wcol[4 * r4 + 3]; }
;         const float la = -(fmaxf(-z, 0.f) + __logf(1.0f + __expf(-fabsf(z)))) * (1.0f / 16.0f);
;         run += la; b[ii] = run; }
;     tot[g * 128 + d] = run;
;     __syncthreads();
	v_mul_f32_e32 v33, v4, v135
	v_fmac_f32_e32 v33, v3, v134
	v_fmac_f32_e32 v33, v11, v136
	v_fmac_f32_e32 v33, v12, v137
	ds_read_b128 v[134:137], v21 offset:848
	v_add_f32_e32 v36, v36, v33
	s_waitcnt lgkmcnt(7)
	v_mul_f32_e32 v33, v8, v139
	v_fmac_f32_e32 v33, v5, v138
	v_fmac_f32_e32 v33, v15, v140
	v_fmac_f32_e32 v33, v16, v141
	ds_read_b128 v[138:141], v21 offset:864
	v_add_f32_e32 v36, v36, v33
	s_waitcnt lgkmcnt(7)
	v_mul_f32_e32 v33, v2, v143
	v_fmac_f32_e32 v33, v1, v142
	v_fmac_f32_e32 v33, v10, v144
	v_fmac_f32_e32 v33, v9, v145
	ds_read_b128 v[142:145], v21 offset:880
	v_add_f32_e32 v32, v36, v33
	v_max_f32_e64 v33, -v32, 0
	v_mul_f32_e64 v32, |v32|, s64
	v_exp_f32_e32 v32, v32
	s_nop 0
	v_add_f32_e32 v32, 1.0, v32
	v_cmp_gt_f32_e32 vcc, s65, v32
	s_nop 1
	v_cndmask_b32_e64 v34, 0, 32, vcc
	v_ldexp_f32 v32, v32, v34
	v_log_f32_e32 v32, v32
	s_nop 0
	v_mul_f32_e32 v34, 0x3f317217, v32
	v_fma_f32 v34, v32, s66, -v34
	v_fmac_f32_e32 v34, 0x3377d1cf, v32
	v_fmac_f32_e32 v34, 0x3f317217, v32
	v_cmp_lt_f32_e64 s[40:41], |v32|, s67
	s_nop 1
	v_cndmask_b32_e64 v32, v32, v34, s[40:41]
	v_cndmask_b32_e32 v34, 0, v252, vcc
	v_sub_f32_e32 v32, v32, v34
	v_add_f32_e32 v32, v33, v32
	v_fmamk_f32 v32, v32, 0xbd800000, v31
	s_waitcnt lgkmcnt(7)
	v_mul_f32_e32 v33, v14, v115
	v_fmac_f32_e32 v33, v13, v114
	v_fmac_f32_e32 v33, v17, v116
	v_fmac_f32_e32 v33, v18, v117
	ds_read_b128 v[114:117], v21 offset:896
	v_add_f32_e32 v33, v19, v33
	s_waitcnt lgkmcnt(7)
	v_mul_f32_e32 v35, v4, v119
	v_fmac_f32_e32 v35, v3, v118
	v_fmac_f32_e32 v35, v11, v120
	v_fmac_f32_e32 v35, v12, v121
	ds_read_b128 v[118:121], v21 offset:912
	v_add_f32_e32 v33, v33, v35
	s_waitcnt lgkmcnt(7)
	v_mul_f32_e32 v35, v8, v123
	v_fmac_f32_e32 v35, v5, v122
	v_fmac_f32_e32 v35, v15, v124
	v_fmac_f32_e32 v35, v16, v125
	ds_read_b128 v[122:125], v21 offset:928
	v_add_f32_e32 v33, v33, v35
	s_waitcnt lgkmcnt(7)
	v_mul_f32_e32 v35, v2, v127
	v_fmac_f32_e32 v35, v1, v126
	v_fmac_f32_e32 v35, v10, v128
	v_fmac_f32_e32 v35, v9, v129
	ds_read_b128 v[126:129], v21 offset:944
	v_add_f32_e32 v33, v33, v35
	v_max_f32_e64 v34, -v33, 0
	v_mul_f32_e64 v33, |v33|, s64
	v_exp_f32_e32 v33, v33
	s_nop 0
	v_add_f32_e32 v33, 1.0, v33
	v_cmp_gt_f32_e32 vcc, s65, v33
	s_nop 1
	v_cndmask_b32_e64 v35, 0, 32, vcc
	v_ldexp_f32 v33, v33, v35
	v_log_f32_e32 v33, v33
	s_nop 0
	v_mul_f32_e32 v35, 0x3f317217, v33
	v_fma_f32 v35, v33, s66, -v35
	v_fmac_f32_e32 v35, 0x3377d1cf, v33
	v_fmac_f32_e32 v35, 0x3f317217, v33
	v_cmp_lt_f32_e64 s[40:41], |v33|, s67
	s_nop 1
	v_cndmask_b32_e64 v33, v33, v35, s[40:41]
	v_cndmask_b32_e32 v35, 0, v252, vcc
	v_sub_f32_e32 v33, v33, v35
	v_add_f32_e32 v33, v34, v33
	v_fmamk_f32 v33, v33, 0xbd800000, v32
	s_waitcnt lgkmcnt(7)
	v_mul_f32_e32 v35, v14, v131
	v_fmac_f32_e32 v35, v13, v130
	v_fmac_f32_e32 v35, v17, v132
	v_fmac_f32_e32 v35, v18, v133
	ds_read_b128 v[130:133], v21 offset:960
	v_add_f32_e32 v38, v19, v35
	s_waitcnt lgkmcnt(7)
	v_mul_f32_e32 v35, v4, v135
	v_fmac_f32_e32 v35, v3, v134
	v_fmac_f32_e32 v35, v11, v136
	v_fmac_f32_e32 v35, v12, v137
	ds_read_b128 v[134:137], v21 offset:976
	v_add_f32_e32 v38, v38, v35
	s_waitcnt lgkmcnt(7)
	v_mul_f32_e32 v35, v8, v139
	v_fmac_f32_e32 v35, v5, v138
	v_fmac_f32_e32 v35, v15, v140
	v_fmac_f32_e32 v35, v16, v141
	ds_read_b128 v[138:141], v21 offset:992
	v_add_f32_e32 v38, v38, v35
	s_waitcnt lgkmcnt(7)
	v_mul_f32_e32 v35, v2, v143
	v_fmac_f32_e32 v35, v1, v142
	v_fmac_f32_e32 v35, v10, v144
	v_fmac_f32_e32 v35, v9, v145
	ds_read_b128 v[142:145], v21 offset:1008
	v_add_f32_e32 v34, v38, v35
	v_max_f32_e64 v35, -v34, 0
	v_mul_f32_e64 v34, |v34|, s64
	v_exp_f32_e32 v34, v34
	s_nop 0
	v_add_f32_e32 v34, 1.0, v34
	v_cmp_gt_f32_e32 vcc, s65, v34
	s_nop 1
	v_cndmask_b32_e64 v36, 0, 32, vcc
	v_ldexp_f32 v34, v34, v36
	v_log_f32_e32 v34, v34
	s_nop 0
	v_mul_f32_e32 v36, 0x3f317217, v34
	v_fma_f32 v36, v34, s66, -v36
	v_fmac_f32_e32 v36, 0x3377d1cf, v34
	v_fmac_f32_e32 v36, 0x3f317217, v34
	v_cmp_lt_f32_e64 s[40:41], |v34|, s67
	s_nop 1
	v_cndmask_b32_e64 v34, v34, v36, s[40:41]
	v_cndmask_b32_e32 v36, 0, v252, vcc
	v_sub_f32_e32 v34, v34, v36
	v_add_f32_e32 v34, v35, v34
	v_fmamk_f32 v34, v34, 0xbd800000, v33
	s_waitcnt lgkmcnt(7)
	v_mul_f32_e32 v35, v14, v115
	v_fmac_f32_e32 v35, v13, v114
	v_fmac_f32_e32 v35, v17, v116
	v_fmac_f32_e32 v35, v18, v117
	v_add_f32_e32 v35, v19, v35
	s_waitcnt lgkmcnt(6)
	v_mul_f32_e32 v37, v4, v119
	v_fmac_f32_e32 v37, v3, v118
	v_fmac_f32_e32 v37, v11, v120
	v_fmac_f32_e32 v37, v12, v121
	v_add_f32_e32 v35, v35, v37
	s_waitcnt lgkmcnt(5)
	v_mul_f32_e32 v37, v8, v123
	v_fmac_f32_e32 v37, v5, v122
	v_fmac_f32_e32 v37, v15, v124
	v_fmac_f32_e32 v37, v16, v125
	v_add_f32_e32 v35, v35, v37
	s_waitcnt lgkmcnt(4)
	v_mul_f32_e32 v37, v2, v127
	v_fmac_f32_e32 v37, v1, v126
	v_fmac_f32_e32 v37, v10, v128
	v_fmac_f32_e32 v37, v9, v129
	v_add_f32_e32 v35, v35, v37
	v_max_f32_e64 v36, -v35, 0
	v_mul_f32_e64 v35, |v35|, s64
	v_exp_f32_e32 v35, v35
	s_nop 0
	v_add_f32_e32 v35, 1.0, v35
	v_cmp_gt_f32_e32 vcc, s65, v35
	s_nop 1
	v_cndmask_b32_e64 v37, 0, 32, vcc
	v_ldexp_f32 v35, v35, v37
	v_log_f32_e32 v35, v35
	s_nop 0
	v_mul_f32_e32 v37, 0x3f317217, v35
	v_fma_f32 v37, v35, s66, -v37
	v_fmac_f32_e32 v37, 0x3377d1cf, v35
	v_fmac_f32_e32 v37, 0x3f317217, v35
	v_cmp_lt_f32_e64 s[40:41], |v35|, s67
	s_nop 1
	v_cndmask_b32_e64 v35, v35, v37, s[40:41]
	v_cndmask_b32_e32 v37, 0, v252, vcc
	v_sub_f32_e32 v35, v35, v37
	v_add_f32_e32 v35, v36, v35
	v_fmamk_f32 v35, v35, 0xbd800000, v34
	s_waitcnt lgkmcnt(3)
	v_mul_f32_e32 v14, v14, v131
	v_fmac_f32_e32 v14, v13, v130
	v_fmac_f32_e32 v14, v17, v132
	v_fmac_f32_e32 v14, v18, v133
	v_add_f32_e32 v13, v19, v14
	s_waitcnt lgkmcnt(2)
	v_mul_f32_e32 v4, v4, v135
	v_fmac_f32_e32 v4, v3, v134
	v_fmac_f32_e32 v4, v11, v136
	v_fmac_f32_e32 v4, v12, v137
	v_add_f32_e32 v3, v13, v4
	s_waitcnt lgkmcnt(1)
	v_mul_f32_e32 v4, v8, v139
	v_fmac_f32_e32 v4, v5, v138
	v_fmac_f32_e32 v4, v15, v140
	v_fmac_f32_e32 v4, v16, v141
	v_add_f32_e32 v3, v3, v4
	s_waitcnt lgkmcnt(0)
	v_mul_f32_e32 v2, v2, v143
	v_fmac_f32_e32 v2, v1, v142
	v_fmac_f32_e32 v2, v10, v144
	v_fmac_f32_e32 v2, v9, v145
	v_add_f32_e32 v1, v3, v2
	v_max_f32_e64 v2, -v1, 0
	v_mul_f32_e64 v1, |v1|, s64
	v_exp_f32_e32 v1, v1
	s_nop 0
	v_add_f32_e32 v1, 1.0, v1
	v_cmp_gt_f32_e32 vcc, s65, v1
	s_nop 1
	v_cndmask_b32_e64 v3, 0, 32, vcc
	v_ldexp_f32 v1, v1, v3
	v_log_f32_e32 v1, v1
	s_nop 0
	v_mul_f32_e32 v3, 0x3f317217, v1
	v_fma_f32 v3, v1, s66, -v3
	v_fmac_f32_e32 v3, 0x3377d1cf, v1
	v_fmac_f32_e32 v3, 0x3f317217, v1
	v_cmp_lt_f32_e64 s[40:41], |v1|, s67
	s_nop 1
	v_cndmask_b32_e64 v1, v1, v3, s[40:41]
	v_cndmask_b32_e32 v3, 0, v252, vcc
	v_sub_f32_e32 v1, v1, v3
	v_add_f32_e32 v1, v2, v1
	v_fmamk_f32 v9, v1, 0xbd800000, v35
	v_lshl_add_u32 v1, v6, 2, 0
	v_add_u32_e32 v1, 0x12000, v1
	v_lshl_add_u32 v2, v7, 9, v1
	ds_write_b32 v2, v9
	s_waitcnt lgkmcnt(0)
	s_barrier
; __device__ __forceinline__ void gla_logdecay(float (&b)[16], float& blast, const LAS float* glrs, const float (&wcol)[16], const float bias, int d, int g, LAS float* tot) {
;     ...
;     __syncthreads();
;     float off = 0.f, all = 0.f;
; #pragma unroll
;     for (int gg = 0; gg < 4; ++gg) { const float tv = tot[gg * 128 + d]; all += tv; if (gg < g) off += tv; }
; #pragma unroll
;     for (int ii = 0; ii < 16; ++ii) b[ii] += off;
;     blast = all;
; __device__ __forceinline__ void gla_stepA(LAS unsigned char* lds, int item, const bf16* proj, const bf16* vtg, const float* glr, const float* W2, const float* b2, bf16* dST, float* decay) {
;     ...
;     if (g == 0) decay[(size_t)item * 128 + d] = __expf(blast);
	ds_read2st64_b32 v[2:3], v1 offset1:2
	ds_read2st64_b32 v[4:5], v1 offset0:4 offset1:6
	v_cmp_gt_u32_e32 vcc, s0, v0
	s_waitcnt lgkmcnt(1)
	v_add_f32_e32 v2, 0, v2
	v_add_f32_e32 v1, v2, v3
	s_waitcnt lgkmcnt(0)
	v_add_f32_e32 v1, v1, v4
	v_add_f32_e32 v8, v1, v5
	s_and_saveexec_b64 s[36:37], vcc
	s_cbranch_execz .LBB0_148
	v_mul_f32_e32 v1, 0x3fb8aa3b, v8
	v_exp_f32_e32 v12, v1
	s_add_u32 s14, s56, s24
	v_mov_b32_e32 v1, v153
	s_addc_u32 s15, s57, s25
	v_lshl_add_u64 v[10:11], v[0:1], 2, s[14:15]
	global_store_dword v[10:11], v12, off
	s_branch .LBB0_148
